# speedup vs baseline: 1.0012x; 1.0012x over previous
; #define GAS __attribute__((address_space(1)))
; __device__ __forceinline__ unsigned f2bf(float f) { return pk2(f, f) & 0xffffu; }
; __device__ __forceinline__ float sigmoidf_(float v) { return __builtin_amdgcn_rcpf(1.f + __builtin_amdgcn_exp2f(-LOG2E * v)); }
; __device__ __forceinline__ void phase_up(int pass) {
;     ...
;     EPI_IDS
;     const float* rr = (const float*)(smem_raw + LDS_RR) + par * 256;
;     GAS char* tb = (GAS char*)act + ((size_t)brow * FFP + (bcol >> 1)) * 2;
;     const unsigned off0 = (unsigned)((wr * 64 + fq * 4) * FFP + wc * 16 + fr) * 2u;
; #pragma unroll
;     for (int ai = 0; ai < 2; ++ai)
; #pragma unroll
;       for (int m = 0; m < 4; ++m)
; #pragma unroll
;         for (int j = 0; j < 4; ++j) {
;           const int rowl = ai * 128 + wr * 64 + m * 16 + fq * 4 + j;
;           const float r = rr[rowl];
; #pragma unroll
;           for (int bj = 0; bj < 2; ++bj) {
;             const float g = acc[ai][bj][m][0][j] * r, u = acc[ai][bj][m][1][j] * r;
;             const float v = g * sigmoidf_(g) * u;
;             *(GAS unsigned short*)(tb + (off0 + (unsigned)(((ai * 128 + m * 16 + j) * FFP + bj * 64) * 2))) = (unsigned short)f2bf(v);
;           }
;         }
.LBB0_85:
	v_and_b32_e32 v174, 15, v170
	v_lshrrev_b32_e32 v175, 8, v170
	v_lshl_or_b32 v175, v175, 6, v174
	v_bfe_u32 v176, v170, 4, 2
	v_bfe_u32 v177, v170, 6, 2
	v_lshlrev_b32_e32 v176, 2, v176
	v_lshl_or_b32 v176, v177, 4, v176
	v_mul_u32_u24_e32 v186, 0xb40, v175
	v_add_lshl_u32 v186, v186, v176, 1
	s_lshl_b32 s18, s37, 10
	s_add_i32 s18, s18, 0x20100
	v_lshl_add_u32 v174, v175, 2, s18
	ds_read_b32 v178, v174
	ds_read_b32 v179, v174 offset:64
	ds_read_b32 v180, v174 offset:128
	ds_read_b32 v181, v174 offset:192
	ds_read_b32 v182, v174 offset:512
	ds_read_b32 v183, v174 offset:576
	ds_read_b32 v184, v174 offset:640
	ds_read_b32 v185, v174 offset:704
	s_lshl_b32 s19, s41, 7
	s_mul_hi_i32 s17, s16, 0xb40
	s_mulk_i32 s16, 0xb40
	s_ashr_i32 s20, s19, 31
	s_add_u32 s16, s16, s19
	s_addc_u32 s17, s17, s20
	s_lshl_b64 s[16:17], s[16:17], 1
	s_add_u32 s16, s35, s16
	s_addc_u32 s17, s36, s17
	s_waitcnt lgkmcnt(0)
	v_mul_f32_e32 v118, v118, v178
	v_mul_f32_e32 v119, v119, v178
	v_mul_f32_e32 v120, v120, v178
	v_mul_f32_e32 v121, v121, v178
	v_mul_f32_e32 v174, 0xbfb8aa3b, v118
	v_mul_f32_e32 v175, 0xbfb8aa3b, v119
	v_mul_f32_e32 v176, 0xbfb8aa3b, v120
	v_mul_f32_e32 v177, 0xbfb8aa3b, v121
	v_exp_f32_e32 v174, v174
	v_exp_f32_e32 v175, v175
	v_exp_f32_e32 v176, v176
	v_exp_f32_e32 v177, v177
	v_mul_f32_e32 v114, v114, v178
	v_mul_f32_e32 v115, v115, v178
	v_mul_f32_e32 v116, v116, v178
	v_mul_f32_e32 v117, v117, v178
	v_add_f32_e32 v174, 1.0, v174
	v_add_f32_e32 v175, 1.0, v175
	v_add_f32_e32 v176, 1.0, v176
	v_add_f32_e32 v177, 1.0, v177
	v_rcp_f32_e32 v174, v174
	v_rcp_f32_e32 v175, v175
	v_rcp_f32_e32 v176, v176
	v_rcp_f32_e32 v177, v177
	v_mul_f32_e32 v118, v118, v174
	v_mul_f32_e32 v119, v119, v175
	v_mul_f32_e32 v120, v120, v176
	v_mul_f32_e32 v121, v121, v177
	v_mul_f32_e32 v114, v114, v118
	v_mul_f32_e32 v115, v115, v119
	v_mul_f32_e32 v116, v116, v120
	v_mul_f32_e32 v117, v117, v121
	v_cvt_pk_bf16_f32 v114, v114, v115
	v_cvt_pk_bf16_f32 v115, v116, v117
	global_store_dwordx2 v186, v[114:115], s[16:17]
	v_mul_f32_e32 v126, v126, v178
	v_mul_f32_e32 v127, v127, v178
	v_mul_f32_e32 v128, v128, v178
	v_mul_f32_e32 v129, v129, v178
	v_mul_f32_e32 v174, 0xbfb8aa3b, v126
	v_mul_f32_e32 v175, 0xbfb8aa3b, v127
	v_mul_f32_e32 v176, 0xbfb8aa3b, v128
	v_mul_f32_e32 v177, 0xbfb8aa3b, v129
	v_exp_f32_e32 v174, v174
	v_exp_f32_e32 v175, v175
	v_exp_f32_e32 v176, v176
	v_exp_f32_e32 v177, v177
	v_mul_f32_e32 v122, v122, v178
	v_mul_f32_e32 v123, v123, v178
	v_mul_f32_e32 v124, v124, v178
	v_mul_f32_e32 v125, v125, v178
	v_add_f32_e32 v174, 1.0, v174
	v_add_f32_e32 v175, 1.0, v175
	v_add_f32_e32 v176, 1.0, v176
	v_add_f32_e32 v177, 1.0, v177
	v_rcp_f32_e32 v174, v174
	v_rcp_f32_e32 v175, v175
	v_rcp_f32_e32 v176, v176
	v_rcp_f32_e32 v177, v177
	v_mul_f32_e32 v126, v126, v174
	v_mul_f32_e32 v127, v127, v175
	v_mul_f32_e32 v128, v128, v176
	v_mul_f32_e32 v129, v129, v177
	v_mul_f32_e32 v122, v122, v126
	v_mul_f32_e32 v123, v123, v127
	v_mul_f32_e32 v124, v124, v128
	v_mul_f32_e32 v125, v125, v129
	v_cvt_pk_bf16_f32 v122, v122, v123
	v_cvt_pk_bf16_f32 v123, v124, v125
	global_store_dwordx2 v186, v[122:123], s[16:17] offset:128
	s_add_u32 s16, s16, 0x16800
	s_addc_u32 s17, s17, 0
	v_mul_f32_e32 v102, v102, v179
	v_mul_f32_e32 v103, v103, v179
	v_mul_f32_e32 v104, v104, v179
	v_mul_f32_e32 v105, v105, v179
	v_mul_f32_e32 v174, 0xbfb8aa3b, v102
	v_mul_f32_e32 v175, 0xbfb8aa3b, v103
	v_mul_f32_e32 v176, 0xbfb8aa3b, v104
	v_mul_f32_e32 v177, 0xbfb8aa3b, v105
	v_exp_f32_e32 v174, v174
	v_exp_f32_e32 v175, v175
	v_exp_f32_e32 v176, v176
	v_exp_f32_e32 v177, v177
	v_mul_f32_e32 v98, v98, v179
	v_mul_f32_e32 v99, v99, v179
	v_mul_f32_e32 v100, v100, v179
	v_mul_f32_e32 v101, v101, v179
	v_add_f32_e32 v174, 1.0, v174
	v_add_f32_e32 v175, 1.0, v175
	v_add_f32_e32 v176, 1.0, v176
	v_add_f32_e32 v177, 1.0, v177
	v_rcp_f32_e32 v174, v174
	v_rcp_f32_e32 v175, v175
	v_rcp_f32_e32 v176, v176
	v_rcp_f32_e32 v177, v177
	v_mul_f32_e32 v102, v102, v174
	v_mul_f32_e32 v103, v103, v175
	v_mul_f32_e32 v104, v104, v176
	v_mul_f32_e32 v105, v105, v177
	v_mul_f32_e32 v98, v98, v102
	v_mul_f32_e32 v99, v99, v103
	v_mul_f32_e32 v100, v100, v104
	v_mul_f32_e32 v101, v101, v105
	v_cvt_pk_bf16_f32 v98, v98, v99
	v_cvt_pk_bf16_f32 v99, v100, v101
	global_store_dwordx2 v186, v[98:99], s[16:17]
	v_mul_f32_e32 v110, v110, v179
	v_mul_f32_e32 v111, v111, v179
	v_mul_f32_e32 v112, v112, v179
	v_mul_f32_e32 v113, v113, v179
	v_mul_f32_e32 v174, 0xbfb8aa3b, v110
	v_mul_f32_e32 v175, 0xbfb8aa3b, v111
	v_mul_f32_e32 v176, 0xbfb8aa3b, v112
	v_mul_f32_e32 v177, 0xbfb8aa3b, v113
	v_exp_f32_e32 v174, v174
	v_exp_f32_e32 v175, v175
	v_exp_f32_e32 v176, v176
	v_exp_f32_e32 v177, v177
	v_mul_f32_e32 v106, v106, v179
	v_mul_f32_e32 v107, v107, v179
	v_mul_f32_e32 v108, v108, v179
	v_mul_f32_e32 v109, v109, v179
	v_add_f32_e32 v174, 1.0, v174
	v_add_f32_e32 v175, 1.0, v175
	v_add_f32_e32 v176, 1.0, v176
	v_add_f32_e32 v177, 1.0, v177
	v_rcp_f32_e32 v174, v174
	v_rcp_f32_e32 v175, v175
	v_rcp_f32_e32 v176, v176
	v_rcp_f32_e32 v177, v177
	v_mul_f32_e32 v110, v110, v174
	v_mul_f32_e32 v111, v111, v175
	v_mul_f32_e32 v112, v112, v176
	v_mul_f32_e32 v113, v113, v177
	v_mul_f32_e32 v106, v106, v110
	v_mul_f32_e32 v107, v107, v111
	v_mul_f32_e32 v108, v108, v112
	v_mul_f32_e32 v109, v109, v113
	v_cvt_pk_bf16_f32 v106, v106, v107
	v_cvt_pk_bf16_f32 v107, v108, v109
	global_store_dwordx2 v186, v[106:107], s[16:17] offset:128
	s_add_u32 s16, s16, 0x16800
	s_addc_u32 s17, s17, 0
	v_mul_f32_e32 v86, v86, v180
	v_mul_f32_e32 v87, v87, v180
	v_mul_f32_e32 v88, v88, v180
	v_mul_f32_e32 v89, v89, v180
; #define GAS __attribute__((address_space(1)))
; __device__ __forceinline__ unsigned f2bf(float f) { return pk2(f, f) & 0xffffu; }
; __device__ __forceinline__ float sigmoidf_(float v) { return __builtin_amdgcn_rcpf(1.f + __builtin_amdgcn_exp2f(-LOG2E * v)); }
; __device__ __forceinline__ void phase_up(int pass) {
;     ...
; #pragma unroll
;     for (int ai = 0; ai < 2; ++ai)
; #pragma unroll
;       for (int m = 0; m < 4; ++m)
; #pragma unroll
;         for (int j = 0; j < 4; ++j) {
;           const int rowl = ai * 128 + wr * 64 + m * 16 + fq * 4 + j;
;           const float r = rr[rowl];
; #pragma unroll
;           for (int bj = 0; bj < 2; ++bj) {
;             const float g = acc[ai][bj][m][0][j] * r, u = acc[ai][bj][m][1][j] * r;
;             const float v = g * sigmoidf_(g) * u;
;             *(GAS unsigned short*)(tb + (off0 + (unsigned)(((ai * 128 + m * 16 + j) * FFP + bj * 64) * 2))) = (unsigned short)f2bf(v);
;           }
;         }
	v_mul_f32_e32 v174, 0xbfb8aa3b, v86
	v_mul_f32_e32 v175, 0xbfb8aa3b, v87
	v_mul_f32_e32 v176, 0xbfb8aa3b, v88
	v_mul_f32_e32 v177, 0xbfb8aa3b, v89
	v_exp_f32_e32 v174, v174
	v_exp_f32_e32 v175, v175
	v_exp_f32_e32 v176, v176
	v_exp_f32_e32 v177, v177
	v_mul_f32_e32 v82, v82, v180
	v_mul_f32_e32 v83, v83, v180
	v_mul_f32_e32 v84, v84, v180
	v_mul_f32_e32 v85, v85, v180
	v_add_f32_e32 v174, 1.0, v174
	v_add_f32_e32 v175, 1.0, v175
	v_add_f32_e32 v176, 1.0, v176
	v_add_f32_e32 v177, 1.0, v177
	v_rcp_f32_e32 v174, v174
	v_rcp_f32_e32 v175, v175
	v_rcp_f32_e32 v176, v176
	v_rcp_f32_e32 v177, v177
	v_mul_f32_e32 v86, v86, v174
	v_mul_f32_e32 v87, v87, v175
	v_mul_f32_e32 v88, v88, v176
	v_mul_f32_e32 v89, v89, v177
	v_mul_f32_e32 v82, v82, v86
	v_mul_f32_e32 v83, v83, v87
	v_mul_f32_e32 v84, v84, v88
	v_mul_f32_e32 v85, v85, v89
	v_cvt_pk_bf16_f32 v82, v82, v83
	v_cvt_pk_bf16_f32 v83, v84, v85
	global_store_dwordx2 v186, v[82:83], s[16:17]
	v_mul_f32_e32 v94, v94, v180
	v_mul_f32_e32 v95, v95, v180
	v_mul_f32_e32 v96, v96, v180
	v_mul_f32_e32 v97, v97, v180
	v_mul_f32_e32 v174, 0xbfb8aa3b, v94
	v_mul_f32_e32 v175, 0xbfb8aa3b, v95
	v_mul_f32_e32 v176, 0xbfb8aa3b, v96
	v_mul_f32_e32 v177, 0xbfb8aa3b, v97
	v_exp_f32_e32 v174, v174
	v_exp_f32_e32 v175, v175
	v_exp_f32_e32 v176, v176
	v_exp_f32_e32 v177, v177
	v_mul_f32_e32 v90, v90, v180
	v_mul_f32_e32 v91, v91, v180
	v_mul_f32_e32 v92, v92, v180
	v_mul_f32_e32 v93, v93, v180
	v_add_f32_e32 v174, 1.0, v174
	v_add_f32_e32 v175, 1.0, v175
	v_add_f32_e32 v176, 1.0, v176
	v_add_f32_e32 v177, 1.0, v177
	v_rcp_f32_e32 v174, v174
	v_rcp_f32_e32 v175, v175
	v_rcp_f32_e32 v176, v176
	v_rcp_f32_e32 v177, v177
	v_mul_f32_e32 v94, v94, v174
	v_mul_f32_e32 v95, v95, v175
	v_mul_f32_e32 v96, v96, v176
	v_mul_f32_e32 v97, v97, v177
	v_mul_f32_e32 v90, v90, v94
	v_mul_f32_e32 v91, v91, v95
	v_mul_f32_e32 v92, v92, v96
	v_mul_f32_e32 v93, v93, v97
	v_cvt_pk_bf16_f32 v90, v90, v91
	v_cvt_pk_bf16_f32 v91, v92, v93
	global_store_dwordx2 v186, v[90:91], s[16:17] offset:128
	s_add_u32 s16, s16, 0x16800
	s_addc_u32 s17, s17, 0
	v_mul_f32_e32 v70, v70, v181
	v_mul_f32_e32 v71, v71, v181
	v_mul_f32_e32 v72, v72, v181
	v_mul_f32_e32 v73, v73, v181
	v_mul_f32_e32 v174, 0xbfb8aa3b, v70
	v_mul_f32_e32 v175, 0xbfb8aa3b, v71
	v_mul_f32_e32 v176, 0xbfb8aa3b, v72
	v_mul_f32_e32 v177, 0xbfb8aa3b, v73
	v_exp_f32_e32 v174, v174
	v_exp_f32_e32 v175, v175
	v_exp_f32_e32 v176, v176
	v_exp_f32_e32 v177, v177
	v_mul_f32_e32 v66, v66, v181
	v_mul_f32_e32 v67, v67, v181
	v_mul_f32_e32 v68, v68, v181
	v_mul_f32_e32 v69, v69, v181
	v_add_f32_e32 v174, 1.0, v174
	v_add_f32_e32 v175, 1.0, v175
	v_add_f32_e32 v176, 1.0, v176
	v_add_f32_e32 v177, 1.0, v177
	v_rcp_f32_e32 v174, v174
	v_rcp_f32_e32 v175, v175
	v_rcp_f32_e32 v176, v176
	v_rcp_f32_e32 v177, v177
	v_mul_f32_e32 v70, v70, v174
	v_mul_f32_e32 v71, v71, v175
	v_mul_f32_e32 v72, v72, v176
	v_mul_f32_e32 v73, v73, v177
	v_mul_f32_e32 v66, v66, v70
	v_mul_f32_e32 v67, v67, v71
	v_mul_f32_e32 v68, v68, v72
	v_mul_f32_e32 v69, v69, v73
	v_cvt_pk_bf16_f32 v66, v66, v67
	v_cvt_pk_bf16_f32 v67, v68, v69
	global_store_dwordx2 v186, v[66:67], s[16:17]
	v_mul_f32_e32 v78, v78, v181
	v_mul_f32_e32 v79, v79, v181
	v_mul_f32_e32 v80, v80, v181
	v_mul_f32_e32 v81, v81, v181
	v_mul_f32_e32 v174, 0xbfb8aa3b, v78
	v_mul_f32_e32 v175, 0xbfb8aa3b, v79
	v_mul_f32_e32 v176, 0xbfb8aa3b, v80
	v_mul_f32_e32 v177, 0xbfb8aa3b, v81
	v_exp_f32_e32 v174, v174
	v_exp_f32_e32 v175, v175
	v_exp_f32_e32 v176, v176
	v_exp_f32_e32 v177, v177
	v_mul_f32_e32 v74, v74, v181
	v_mul_f32_e32 v75, v75, v181
	v_mul_f32_e32 v76, v76, v181
	v_mul_f32_e32 v77, v77, v181
	v_add_f32_e32 v174, 1.0, v174
	v_add_f32_e32 v175, 1.0, v175
	v_add_f32_e32 v176, 1.0, v176
	v_add_f32_e32 v177, 1.0, v177
	v_rcp_f32_e32 v174, v174
	v_rcp_f32_e32 v175, v175
	v_rcp_f32_e32 v176, v176
	v_rcp_f32_e32 v177, v177
	v_mul_f32_e32 v78, v78, v174
	v_mul_f32_e32 v79, v79, v175
	v_mul_f32_e32 v80, v80, v176
	v_mul_f32_e32 v81, v81, v177
	v_mul_f32_e32 v74, v74, v78
	v_mul_f32_e32 v75, v75, v79
	v_mul_f32_e32 v76, v76, v80
	v_mul_f32_e32 v77, v77, v81
	v_cvt_pk_bf16_f32 v74, v74, v75
	v_cvt_pk_bf16_f32 v75, v76, v77
	global_store_dwordx2 v186, v[74:75], s[16:17] offset:128
	s_add_u32 s16, s16, 0x70800
	s_addc_u32 s17, s17, 0
	v_mul_f32_e32 v54, v54, v182
	v_mul_f32_e32 v55, v55, v182
	v_mul_f32_e32 v56, v56, v182
	v_mul_f32_e32 v57, v57, v182
	v_mul_f32_e32 v174, 0xbfb8aa3b, v54
	v_mul_f32_e32 v175, 0xbfb8aa3b, v55
	v_mul_f32_e32 v176, 0xbfb8aa3b, v56
	v_mul_f32_e32 v177, 0xbfb8aa3b, v57
	v_exp_f32_e32 v174, v174
	v_exp_f32_e32 v175, v175
	v_exp_f32_e32 v176, v176
	v_exp_f32_e32 v177, v177
	v_mul_f32_e32 v50, v50, v182
	v_mul_f32_e32 v51, v51, v182
	v_mul_f32_e32 v52, v52, v182
	v_mul_f32_e32 v53, v53, v182
	v_add_f32_e32 v174, 1.0, v174
	v_add_f32_e32 v175, 1.0, v175
	v_add_f32_e32 v176, 1.0, v176
	v_add_f32_e32 v177, 1.0, v177
	v_rcp_f32_e32 v174, v174
	v_rcp_f32_e32 v175, v175
	v_rcp_f32_e32 v176, v176
	v_rcp_f32_e32 v177, v177
	v_mul_f32_e32 v54, v54, v174
	v_mul_f32_e32 v55, v55, v175
	v_mul_f32_e32 v56, v56, v176
	v_mul_f32_e32 v57, v57, v177
	v_mul_f32_e32 v50, v50, v54
	v_mul_f32_e32 v51, v51, v55
	v_mul_f32_e32 v52, v52, v56
	v_mul_f32_e32 v53, v53, v57
	v_cvt_pk_bf16_f32 v50, v50, v51
	v_cvt_pk_bf16_f32 v51, v52, v53
	global_store_dwordx2 v186, v[50:51], s[16:17]
	v_mul_f32_e32 v62, v62, v182
	v_mul_f32_e32 v63, v63, v182
	v_mul_f32_e32 v64, v64, v182
	v_mul_f32_e32 v65, v65, v182
	v_mul_f32_e32 v174, 0xbfb8aa3b, v62
	v_mul_f32_e32 v175, 0xbfb8aa3b, v63
	v_mul_f32_e32 v176, 0xbfb8aa3b, v64
	v_mul_f32_e32 v177, 0xbfb8aa3b, v65
	v_exp_f32_e32 v174, v174
; #define GAS __attribute__((address_space(1)))
; __device__ __forceinline__ unsigned f2bf(float f) { return pk2(f, f) & 0xffffu; }
; __device__ __forceinline__ float sigmoidf_(float v) { return __builtin_amdgcn_rcpf(1.f + __builtin_amdgcn_exp2f(-LOG2E * v)); }
; __device__ __forceinline__ void phase_up(int pass) {
;     ...
; #pragma unroll
;     for (int ai = 0; ai < 2; ++ai)
; #pragma unroll
;       for (int m = 0; m < 4; ++m)
; #pragma unroll
;         for (int j = 0; j < 4; ++j) {
;           const int rowl = ai * 128 + wr * 64 + m * 16 + fq * 4 + j;
;           const float r = rr[rowl];
; #pragma unroll
;           for (int bj = 0; bj < 2; ++bj) {
;             const float g = acc[ai][bj][m][0][j] * r, u = acc[ai][bj][m][1][j] * r;
;             const float v = g * sigmoidf_(g) * u;
;             *(GAS unsigned short*)(tb + (off0 + (unsigned)(((ai * 128 + m * 16 + j) * FFP + bj * 64) * 2))) = (unsigned short)f2bf(v);
;           }
;         }
	v_exp_f32_e32 v175, v175
	v_exp_f32_e32 v176, v176
	v_exp_f32_e32 v177, v177
	v_mul_f32_e32 v58, v58, v182
	v_mul_f32_e32 v59, v59, v182
	v_mul_f32_e32 v60, v60, v182
	v_mul_f32_e32 v61, v61, v182
	v_add_f32_e32 v174, 1.0, v174
	v_add_f32_e32 v175, 1.0, v175
	v_add_f32_e32 v176, 1.0, v176
	v_add_f32_e32 v177, 1.0, v177
	v_rcp_f32_e32 v174, v174
	v_rcp_f32_e32 v175, v175
	v_rcp_f32_e32 v176, v176
	v_rcp_f32_e32 v177, v177
	v_mul_f32_e32 v62, v62, v174
	v_mul_f32_e32 v63, v63, v175
	v_mul_f32_e32 v64, v64, v176
	v_mul_f32_e32 v65, v65, v177
	v_mul_f32_e32 v58, v58, v62
	v_mul_f32_e32 v59, v59, v63
	v_mul_f32_e32 v60, v60, v64
	v_mul_f32_e32 v61, v61, v65
	v_cvt_pk_bf16_f32 v58, v58, v59
	v_cvt_pk_bf16_f32 v59, v60, v61
	global_store_dwordx2 v186, v[58:59], s[16:17] offset:128
	s_add_u32 s16, s16, 0x16800
	s_addc_u32 s17, s17, 0
	v_mul_f32_e32 v42, v42, v183
	v_mul_f32_e32 v43, v43, v183
	v_mul_f32_e32 v44, v44, v183
	v_mul_f32_e32 v45, v45, v183
	v_mul_f32_e32 v174, 0xbfb8aa3b, v42
	v_mul_f32_e32 v175, 0xbfb8aa3b, v43
	v_mul_f32_e32 v176, 0xbfb8aa3b, v44
	v_mul_f32_e32 v177, 0xbfb8aa3b, v45
	v_exp_f32_e32 v174, v174
	v_exp_f32_e32 v175, v175
	v_exp_f32_e32 v176, v176
	v_exp_f32_e32 v177, v177
	v_mul_f32_e32 v34, v34, v183
	v_mul_f32_e32 v35, v35, v183
	v_mul_f32_e32 v36, v36, v183
	v_mul_f32_e32 v37, v37, v183
	v_add_f32_e32 v174, 1.0, v174
	v_add_f32_e32 v175, 1.0, v175
	v_add_f32_e32 v176, 1.0, v176
	v_add_f32_e32 v177, 1.0, v177
	v_rcp_f32_e32 v174, v174
	v_rcp_f32_e32 v175, v175
	v_rcp_f32_e32 v176, v176
	v_rcp_f32_e32 v177, v177
	v_mul_f32_e32 v42, v42, v174
	v_mul_f32_e32 v43, v43, v175
	v_mul_f32_e32 v44, v44, v176
	v_mul_f32_e32 v45, v45, v177
	v_mul_f32_e32 v34, v34, v42
	v_mul_f32_e32 v35, v35, v43
	v_mul_f32_e32 v36, v36, v44
	v_mul_f32_e32 v37, v37, v45
	v_cvt_pk_bf16_f32 v34, v34, v35
	v_cvt_pk_bf16_f32 v35, v36, v37
	global_store_dwordx2 v186, v[34:35], s[16:17]
	v_mul_f32_e32 v46, v46, v183
	v_mul_f32_e32 v47, v47, v183
	v_mul_f32_e32 v48, v48, v183
	v_mul_f32_e32 v49, v49, v183
	v_mul_f32_e32 v174, 0xbfb8aa3b, v46
	v_mul_f32_e32 v175, 0xbfb8aa3b, v47
	v_mul_f32_e32 v176, 0xbfb8aa3b, v48
	v_mul_f32_e32 v177, 0xbfb8aa3b, v49
	v_exp_f32_e32 v174, v174
	v_exp_f32_e32 v175, v175
	v_exp_f32_e32 v176, v176
	v_exp_f32_e32 v177, v177
	v_mul_f32_e32 v38, v38, v183
	v_mul_f32_e32 v39, v39, v183
	v_mul_f32_e32 v40, v40, v183
	v_mul_f32_e32 v41, v41, v183
	v_add_f32_e32 v174, 1.0, v174
	v_add_f32_e32 v175, 1.0, v175
	v_add_f32_e32 v176, 1.0, v176
	v_add_f32_e32 v177, 1.0, v177
	v_rcp_f32_e32 v174, v174
	v_rcp_f32_e32 v175, v175
	v_rcp_f32_e32 v176, v176
	v_rcp_f32_e32 v177, v177
	v_mul_f32_e32 v46, v46, v174
	v_mul_f32_e32 v47, v47, v175
	v_mul_f32_e32 v48, v48, v176
	v_mul_f32_e32 v49, v49, v177
	v_mul_f32_e32 v38, v38, v46
	v_mul_f32_e32 v39, v39, v47
	v_mul_f32_e32 v40, v40, v48
	v_mul_f32_e32 v41, v41, v49
	v_cvt_pk_bf16_f32 v38, v38, v39
	v_cvt_pk_bf16_f32 v39, v40, v41
	global_store_dwordx2 v186, v[38:39], s[16:17] offset:128
	s_add_u32 s16, s16, 0x16800
	s_addc_u32 s17, s17, 0
	v_mul_f32_e32 v22, v22, v184
	v_mul_f32_e32 v23, v23, v184
	v_mul_f32_e32 v24, v24, v184
	v_mul_f32_e32 v25, v25, v184
	v_mul_f32_e32 v174, 0xbfb8aa3b, v22
	v_mul_f32_e32 v175, 0xbfb8aa3b, v23
	v_mul_f32_e32 v176, 0xbfb8aa3b, v24
	v_mul_f32_e32 v177, 0xbfb8aa3b, v25
	v_exp_f32_e32 v174, v174
	v_exp_f32_e32 v175, v175
	v_exp_f32_e32 v176, v176
	v_exp_f32_e32 v177, v177
	v_mul_f32_e32 v18, v18, v184
	v_mul_f32_e32 v19, v19, v184
	v_mul_f32_e32 v20, v20, v184
	v_mul_f32_e32 v21, v21, v184
	v_add_f32_e32 v174, 1.0, v174
	v_add_f32_e32 v175, 1.0, v175
	v_add_f32_e32 v176, 1.0, v176
	v_add_f32_e32 v177, 1.0, v177
	v_rcp_f32_e32 v174, v174
	v_rcp_f32_e32 v175, v175
	v_rcp_f32_e32 v176, v176
	v_rcp_f32_e32 v177, v177
	v_mul_f32_e32 v22, v22, v174
	v_mul_f32_e32 v23, v23, v175
	v_mul_f32_e32 v24, v24, v176
	v_mul_f32_e32 v25, v25, v177
	v_mul_f32_e32 v18, v18, v22
	v_mul_f32_e32 v19, v19, v23
	v_mul_f32_e32 v20, v20, v24
	v_mul_f32_e32 v21, v21, v25
	v_cvt_pk_bf16_f32 v18, v18, v19
	v_cvt_pk_bf16_f32 v19, v20, v21
	global_store_dwordx2 v186, v[18:19], s[16:17]
	v_mul_f32_e32 v30, v30, v184
	v_mul_f32_e32 v31, v31, v184
	v_mul_f32_e32 v32, v32, v184
	v_mul_f32_e32 v33, v33, v184
	v_mul_f32_e32 v174, 0xbfb8aa3b, v30
	v_mul_f32_e32 v175, 0xbfb8aa3b, v31
	v_mul_f32_e32 v176, 0xbfb8aa3b, v32
	v_mul_f32_e32 v177, 0xbfb8aa3b, v33
; #define GAS __attribute__((address_space(1)))
; __device__ __forceinline__ unsigned f2bf(float f) { return pk2(f, f) & 0xffffu; }
; __device__ __forceinline__ float sigmoidf_(float v) { return __builtin_amdgcn_rcpf(1.f + __builtin_amdgcn_exp2f(-LOG2E * v)); }
; __device__ __forceinline__ void load_rr(const GAS float* ssq, int brow, int par) {
;     ...
;   if (tx < 256) {
;     const GAS f32x4* s = (const GAS f32x4*)(ssq + (size_t)(brow + tx) * 16);
;     f32x4 a = s[0], b = s[1], c = s[2], d = s[3];
;     float t = ((a.x + a.y) + (a.z + a.w)) + ((b.x + b.y) + (b.z + b.w)) + ((c.x + c.y) + (c.z + c.w)) + ((d.x + d.y) + (d.z + d.w));
;     rr[tx] = rsqrtf(t * (1.f / DM) + EPS);
;   }
; __device__ __forceinline__ void phase_up(int pass) {
;     ...
; #pragma unroll
;     for (int ai = 0; ai < 2; ++ai)
; #pragma unroll
;       for (int m = 0; m < 4; ++m)
; #pragma unroll
;         for (int j = 0; j < 4; ++j) {
;           const int rowl = ai * 128 + wr * 64 + m * 16 + fq * 4 + j;
;           const float r = rr[rowl];
; #pragma unroll
;           for (int bj = 0; bj < 2; ++bj) {
;             const float g = acc[ai][bj][m][0][j] * r, u = acc[ai][bj][m][1][j] * r;
;             const float v = g * sigmoidf_(g) * u;
;             *(GAS unsigned short*)(tb + (off0 + (unsigned)(((ai * 128 + m * 16 + j) * FFP + bj * 64) * 2))) = (unsigned short)f2bf(v);
;           }
;         }
	v_exp_f32_e32 v174, v174
	v_exp_f32_e32 v175, v175
	v_exp_f32_e32 v176, v176
	v_exp_f32_e32 v177, v177
	v_mul_f32_e32 v26, v26, v184
	v_mul_f32_e32 v27, v27, v184
	v_mul_f32_e32 v28, v28, v184
	v_mul_f32_e32 v29, v29, v184
	v_add_f32_e32 v174, 1.0, v174
	v_add_f32_e32 v175, 1.0, v175
	v_add_f32_e32 v176, 1.0, v176
	v_add_f32_e32 v177, 1.0, v177
	v_rcp_f32_e32 v174, v174
	v_rcp_f32_e32 v175, v175
	v_rcp_f32_e32 v176, v176
	v_rcp_f32_e32 v177, v177
	v_mul_f32_e32 v30, v30, v174
	v_mul_f32_e32 v31, v31, v175
	v_mul_f32_e32 v32, v32, v176
	v_mul_f32_e32 v33, v33, v177
	v_mul_f32_e32 v26, v26, v30
	v_mul_f32_e32 v27, v27, v31
	v_mul_f32_e32 v28, v28, v32
	v_mul_f32_e32 v29, v29, v33
	v_cvt_pk_bf16_f32 v26, v26, v27
	v_cvt_pk_bf16_f32 v27, v28, v29
	global_store_dwordx2 v186, v[26:27], s[16:17] offset:128
	s_add_u32 s16, s16, 0x16800
	s_addc_u32 s17, s17, 0
	v_mul_f32_e32 v10, v10, v185
	v_mul_f32_e32 v11, v11, v185
	v_mul_f32_e32 v12, v12, v185
	v_mul_f32_e32 v13, v13, v185
	v_mul_f32_e32 v174, 0xbfb8aa3b, v10
	v_mul_f32_e32 v175, 0xbfb8aa3b, v11
	v_mul_f32_e32 v176, 0xbfb8aa3b, v12
	v_mul_f32_e32 v177, 0xbfb8aa3b, v13
	v_exp_f32_e32 v174, v174
	v_exp_f32_e32 v175, v175
	v_exp_f32_e32 v176, v176
	v_exp_f32_e32 v177, v177
	v_mul_f32_e32 v2, v2, v185
	v_mul_f32_e32 v3, v3, v185
	v_mul_f32_e32 v4, v4, v185
	v_mul_f32_e32 v5, v5, v185
	v_add_f32_e32 v174, 1.0, v174
	v_add_f32_e32 v175, 1.0, v175
	v_add_f32_e32 v176, 1.0, v176
	v_add_f32_e32 v177, 1.0, v177
	v_rcp_f32_e32 v174, v174
	v_rcp_f32_e32 v175, v175
	v_rcp_f32_e32 v176, v176
	v_rcp_f32_e32 v177, v177
	v_mul_f32_e32 v10, v10, v174
	v_mul_f32_e32 v11, v11, v175
	v_mul_f32_e32 v12, v12, v176
	v_mul_f32_e32 v13, v13, v177
	v_mul_f32_e32 v2, v2, v10
	v_mul_f32_e32 v3, v3, v11
	v_mul_f32_e32 v4, v4, v12
	v_mul_f32_e32 v5, v5, v13
	v_cvt_pk_bf16_f32 v2, v2, v3
	v_cvt_pk_bf16_f32 v3, v4, v5
	global_store_dwordx2 v186, v[2:3], s[16:17]
	v_mul_f32_e32 v14, v14, v185
	v_mul_f32_e32 v15, v15, v185
	v_mul_f32_e32 v16, v16, v185
	v_mul_f32_e32 v17, v17, v185
	v_mul_f32_e32 v174, 0xbfb8aa3b, v14
	v_mul_f32_e32 v175, 0xbfb8aa3b, v15
	v_mul_f32_e32 v176, 0xbfb8aa3b, v16
	v_mul_f32_e32 v177, 0xbfb8aa3b, v17
	v_exp_f32_e32 v174, v174
	v_exp_f32_e32 v175, v175
	v_exp_f32_e32 v176, v176
	v_exp_f32_e32 v177, v177
	v_mul_f32_e32 v6, v6, v185
	v_mul_f32_e32 v7, v7, v185
	v_mul_f32_e32 v8, v8, v185
	v_mul_f32_e32 v9, v9, v185
	v_add_f32_e32 v174, 1.0, v174
	v_add_f32_e32 v175, 1.0, v175
	v_add_f32_e32 v176, 1.0, v176
	v_add_f32_e32 v177, 1.0, v177
	v_rcp_f32_e32 v174, v174
	v_rcp_f32_e32 v175, v175
	v_rcp_f32_e32 v176, v176
	v_rcp_f32_e32 v177, v177
	v_mul_f32_e32 v14, v14, v174
	v_mul_f32_e32 v15, v15, v175
	v_mul_f32_e32 v16, v16, v176
	v_mul_f32_e32 v17, v17, v177
	v_mul_f32_e32 v6, v6, v14
	v_mul_f32_e32 v7, v7, v15
	v_mul_f32_e32 v8, v8, v16
	v_mul_f32_e32 v9, v9, v17
	v_cvt_pk_bf16_f32 v6, v6, v7
	v_cvt_pk_bf16_f32 v7, v8, v9
	global_store_dwordx2 v186, v[6:7], s[16:17] offset:128
	s_and_b64 vcc, exec, s[14:15]
	s_cbranch_vccnz .Lup0_rr_skip
	v_cmp_gt_i32_e32 vcc, s34, v170
	s_and_saveexec_b64 s[20:21], vcc
	s_cbranch_execz .Lup0_rr_done
	s_lshl_b32 s17, s37, 10
	s_xor_b32 s17, s17, 0x400
	s_addk_i32 s17, 0x100
	v_lshl_add_u32 v130, v170, 2, s17
	v_add_u32_e32 v130, 0x20000, v130
	s_waitcnt vmcnt(22)
	v_mov_b32_e32 v132, v189
	v_mov_b32_e32 v133, v190
	v_mov_b32_e32 v189, v191
	v_mov_b32_e32 v190, v193
	v_mov_b32_e32 v191, v194
	v_mov_b32_e32 v193, v195
	v_pk_add_f32 v[132:133], v[132:133], v[188:189]
	v_pk_add_f32 v[188:189], v[190:191], v[192:193]
	v_pk_add_f32 v[132:133], v[132:133], v[132:133] op_sel:[0,1] op_sel_hi:[1,0]
	v_pk_add_f32 v[188:189], v[188:189], v[188:189] op_sel:[0,1] op_sel_hi:[1,0]
	v_add_f32_e32 v194, v196, v197
	v_add_f32_e32 v196, v198, v199
	v_mov_b32_e32 v195, v202
	v_mov_b32_e32 v197, v203
	v_mov_b32_e32 v133, v200
	v_mov_b32_e32 v189, v201
	v_pk_add_f32 v[190:191], v[194:195], v[196:197]
	v_pk_add_f32 v[132:133], v[132:133], v[188:189]
	s_nop 0
	v_pk_add_f32 v[132:133], v[132:133], v[190:191]
	s_nop 0
	v_add_f32_e32 v132, v132, v133
	v_fmamk_f32 v132, v132, 0x3a800000, v135
	v_mul_f32_e32 v133, 0x4b800000, v132
	v_cmp_gt_f32_e32 vcc, s39, v132
	s_nop 1
	v_cndmask_b32_e32 v132, v132, v133, vcc
	v_rsq_f32_e32 v132, v132
	s_nop 0
	v_mul_f32_e32 v133, 0x45800000, v132
	v_cndmask_b32_e32 v132, v132, v133, vcc
	ds_write_b32 v130, v132

; #define GAS __attribute__((address_space(1)))
; #define WAIT_V(n) asm volatile("s_waitcnt vmcnt(" #n ")" ::: "memory")
; #define BAR __builtin_amdgcn_s_barrier()
; template <int K, int LD = K>
; __device__ __forceinline__ void gemm_main(const GAS bf16* A, const GAS bf16* Bt, int brow, int bcol, f32x4 (&acc)[2][2][4][2]) {
;     ...
;   const int wid = tid_ >> 6, lane = tid_ & 63, wr = wid >> 2, wc = wid & 3, fr = lane & 15, fq = lane >> 4;
; #pragma unroll
;   for (int a = 0; a < 2; ++a)
; #pragma unroll
;     for (int b = 0; b < 2; ++b)
; #pragma unroll
;       for (int m = 0; m < 4; ++m)
; #pragma unroll
;         for (int n = 0; n < 2; ++n) acc[a][b][m][n] = f32x4{0.f, 0.f, 0.f, 0.f};
;   bf16x8 At[4][2], B0[2][2], B1[2][2];
;   unsigned so0, so1;
;   { int r_, c_; stage_rc(tid_ * 16, r_, c_); so0 = (unsigned)(r_ * LD + c_) * 2u; stage_rc(tid_ * 16 + 8192, r_, c_); so1 = (unsigned)(r_ * LD + c_) * 2u; }
;   const GAS char* pA0 = (const GAS char*)A + (long)brow * LD * 2; const GAS char* pA1 = pA0 + (long)HALF * LD * 2;
;   const GAS char* pB0 = (const GAS char*)Bt + (long)bcol * LD * 2; const GAS char* pB1 = pB0 + (long)HALF * LD * 2;
;   asm volatile("" : "+s"(pA0), "+s"(pA1), "+s"(pB0), "+s"(pB1));
;   constexpr int nt = K / BK;
;   static_assert(K % 128 == 0 && K >= 256, "K");
;   if (wr == 1) BAR;
;   WAIT_V(0); BAR;
;   BAR;
.LBB0_88:
	s_or_b64 exec, exec, s[24:25]
	v_bfe_i32 v7, v136, 27, 1
	v_lshlrev_b32_e32 v5, 4, v136
	v_lshrrev_b32_e32 v7, 22, v7
	v_add_u32_e32 v7, v5, v7
	v_and_b32_e32 v7, 0xfffffc00, v7
	v_sub_u32_e32 v7, v5, v7
	v_lshrrev_b32_e32 v8, 4, v7
	v_bitop3_b32 v8, v8, v7, 32 bitop3:0x6c
	v_ashrrev_i32_e32 v7, 31, v7
	v_ashrrev_i32_e32 v6, 31, v136
	v_lshrrev_b32_e32 v7, 26, v7
	v_lshrrev_b32_e32 v6, 26, v6
	v_add_u32_e32 v7, v8, v7
	v_add_u32_e32 v6, v136, v6
	v_ashrrev_i32_e32 v7, 6, v7
	v_ashrrev_i32_e32 v6, 6, v6
	v_mul_i32_i24_e32 v10, 64, v7
	v_lshlrev_b32_e32 v9, 3, v6
	v_lshlrev_b32_e32 v6, 5, v6
	v_sub_u32_e32 v8, v8, v10
	v_and_b32_e32 v9, 0x1ffff0, v9
	v_and_b32_e32 v6, 32, v6
	v_ashrrev_i16_sdwa v8, v134, sext(v8) dst_sel:DWORD dst_unused:UNUSED_PAD src0_sel:DWORD src1_sel:BYTE_0
	v_add_u32_sdwa v6, v6, sext(v8) dst_sel:DWORD dst_unused:UNUSED_PAD src0_sel:DWORD src1_sel:WORD_0
	v_add_lshl_u32 v7, v7, v9, 11
	v_lshl_add_u32 v130, v6, 1, v7
	v_add_u32_e32 v6, 0x2000, v5
	v_ashrrev_i32_e32 v7, 31, v6
	v_lshrrev_b32_e32 v7, 22, v7
	v_add_u32_e32 v7, v6, v7
	v_ashrrev_i32_e32 v7, 10, v7
	v_mul_i32_i24_e32 v8, 0x400, v7
	v_sub_u32_e32 v6, v6, v8
	v_lshrrev_b32_e32 v8, 4, v6
	v_bitop3_b32 v6, v8, v6, 32 bitop3:0x6c
	v_ashrrev_i32_e32 v9, 31, v6
	v_lshrrev_b32_e32 v9, 26, v9
	v_add_u32_e32 v9, v6, v9
	v_lshrrev_b32_e32 v10, 6, v9
	v_and_b32_e32 v9, 0xc0, v9
	v_lshlrev_b32_e32 v8, 3, v7
	v_lshlrev_b32_e32 v7, 5, v7
	v_sub_u32_e32 v6, v6, v9
	v_and_b32_e32 v8, 0x1ffff0, v8
	v_and_b32_e32 v7, 32, v7
	v_ashrrev_i16_sdwa v6, v134, sext(v6) dst_sel:DWORD dst_unused:UNUSED_PAD src0_sel:DWORD src1_sel:BYTE_0
	v_add_u32_sdwa v6, v7, sext(v6) dst_sel:DWORD dst_unused:UNUSED_PAD src0_sel:DWORD src1_sel:WORD_0
	v_add_lshl_u32 v7, v10, v8, 11
	v_and_b32_e32 v3, 15, v136
	v_lshl_add_u32 v132, v6, 1, v7
	v_lshlrev_b32_e32 v6, 2, v136
	v_and_b32_e32 v4, 48, v136
	v_lshlrev_b32_e32 v3, 6, v3
	v_and_b32_e32 v6, 32, v6
	v_lshlrev_b32_e32 v11, 6, v136
	s_waitcnt vmcnt(22)
	v_bitop3_b32 v3, v3, v6, v4 bitop3:0x36
	v_lshlrev_b32_e32 v13, 13, v2
	v_and_or_b32 v2, v11, s38, v4
	v_add_u32_e32 v7, s29, v3
	v_add_u32_e32 v8, s30, v3
	v_add_u32_e32 v9, s31, v3
	v_add_u32_e32 v10, s33, v3
	v_and_b32_e32 v12, 0x3000, v11
	v_add_u32_e32 v3, 0x100, v3
	v_xad_u32 v4, v2, v6, s34
	v_or_b32_e32 v6, 0x800, v13
	v_or_b32_e32 v11, 0x1000, v13
	v_or_b32_e32 v14, 0x1800, v13
	v_mov_b32_e32 v2, 0
	v_add_u32_e32 v145, 0x100, v5
	v_add_u32_e32 v146, s29, v5
	v_add_u32_e32 v147, s30, v5
	v_add_u32_e32 v148, s31, v5
	v_add_u32_e32 v149, s33, v5
	v_mov_b32_e32 v133, v131
	s_mov_b32 s17, -2
	v_add_u32_e32 v144, v7, v12
	v_add_u32_e32 v140, v3, v13
	v_add_u32_e32 v139, v4, v6
	v_add_u32_e32 v138, v4, v11
	v_add_u32_e32 v137, v4, v14
	v_add_u32_e32 v143, v8, v12
	v_add_u32_e32 v142, v9, v12
	v_add_u32_e32 v141, v10, v12
	v_mov_b32_e32 v3, v2
	v_mov_b32_e32 v4, v2
	v_mov_b32_e32 v5, v2
	v_mov_b32_e32 v6, v2
	v_mov_b32_e32 v7, v2
	v_mov_b32_e32 v8, v2
	v_mov_b32_e32 v9, v2
	v_mov_b32_e32 v10, v2
	v_mov_b32_e32 v11, v2
	v_mov_b32_e32 v12, v2
	v_mov_b32_e32 v13, v2
	v_mov_b32_e32 v14, v2
	v_mov_b32_e32 v15, v2
	v_mov_b32_e32 v16, v2
	v_mov_b32_e32 v17, v2
	v_mov_b32_e32 v18, v2
	v_mov_b32_e32 v19, v2
	v_mov_b32_e32 v20, v2
	v_mov_b32_e32 v21, v2
	v_mov_b32_e32 v22, v2
	v_mov_b32_e32 v23, v2
	v_mov_b32_e32 v24, v2
	v_mov_b32_e32 v25, v2
	v_mov_b32_e32 v26, v2
	v_mov_b32_e32 v27, v2
	v_mov_b32_e32 v28, v2
	v_mov_b32_e32 v29, v2
	v_mov_b32_e32 v30, v2
	v_mov_b32_e32 v31, v2
	v_mov_b32_e32 v32, v2
	v_mov_b32_e32 v33, v2
	v_mov_b32_e32 v34, v2
	v_mov_b32_e32 v35, v2
	v_mov_b32_e32 v36, v2
	v_mov_b32_e32 v37, v2
	v_mov_b32_e32 v38, v2
	v_mov_b32_e32 v39, v2
	v_mov_b32_e32 v40, v2
	v_mov_b32_e32 v41, v2
	v_mov_b32_e32 v42, v2
	v_mov_b32_e32 v43, v2
	v_mov_b32_e32 v44, v2
	v_mov_b32_e32 v45, v2
	v_mov_b32_e32 v46, v2
	v_mov_b32_e32 v47, v2
	v_mov_b32_e32 v48, v2
	v_mov_b32_e32 v49, v2
	v_mov_b32_e32 v50, v2
	v_mov_b32_e32 v51, v2
	v_mov_b32_e32 v52, v2
	v_mov_b32_e32 v53, v2
	v_mov_b32_e32 v54, v2
	v_mov_b32_e32 v55, v2
	v_mov_b32_e32 v56, v2
	v_mov_b32_e32 v57, v2
	v_mov_b32_e32 v58, v2
	v_mov_b32_e32 v59, v2
	v_mov_b32_e32 v60, v2
	v_mov_b32_e32 v61, v2
	v_mov_b32_e32 v62, v2
	v_mov_b32_e32 v63, v2
	v_mov_b32_e32 v64, v2
	v_mov_b32_e32 v65, v2
	v_mov_b32_e32 v66, v2
	v_mov_b32_e32 v67, v2
	v_mov_b32_e32 v68, v2
	v_mov_b32_e32 v69, v2
	v_mov_b32_e32 v70, v2
	v_mov_b32_e32 v71, v2
	v_mov_b32_e32 v72, v2
	v_mov_b32_e32 v73, v2
	v_mov_b32_e32 v74, v2
	v_mov_b32_e32 v75, v2
	v_mov_b32_e32 v76, v2
	v_mov_b32_e32 v77, v2
	v_mov_b32_e32 v78, v2
	v_mov_b32_e32 v79, v2
	v_mov_b32_e32 v80, v2
	v_mov_b32_e32 v81, v2
	v_mov_b32_e32 v82, v2
	v_mov_b32_e32 v83, v2
	v_mov_b32_e32 v84, v2
	v_mov_b32_e32 v85, v2
	v_mov_b32_e32 v86, v2
	v_mov_b32_e32 v87, v2
	v_mov_b32_e32 v88, v2
	v_mov_b32_e32 v89, v2
	v_mov_b32_e32 v90, v2
	v_mov_b32_e32 v91, v2
	v_mov_b32_e32 v92, v2
	v_mov_b32_e32 v93, v2
	v_mov_b32_e32 v94, v2
	v_mov_b32_e32 v95, v2
	v_mov_b32_e32 v96, v2
	v_mov_b32_e32 v97, v2
	v_mov_b32_e32 v98, v2
	v_mov_b32_e32 v99, v2
	v_mov_b32_e32 v100, v2
	v_mov_b32_e32 v101, v2
	v_mov_b32_e32 v102, v2
	v_mov_b32_e32 v103, v2
	v_mov_b32_e32 v104, v2
	v_mov_b32_e32 v105, v2
	v_mov_b32_e32 v106, v2
	v_mov_b32_e32 v107, v2
	v_mov_b32_e32 v108, v2
	v_mov_b32_e32 v109, v2
	v_mov_b32_e32 v110, v2
	v_mov_b32_e32 v111, v2
	v_mov_b32_e32 v112, v2
	v_mov_b32_e32 v113, v2
	v_mov_b32_e32 v114, v2
	v_mov_b32_e32 v115, v2
	v_mov_b32_e32 v116, v2
	v_mov_b32_e32 v117, v2
	v_mov_b32_e32 v118, v2
	v_mov_b32_e32 v119, v2
	v_mov_b32_e32 v120, v2
	v_mov_b32_e32 v121, v2
	v_mov_b32_e32 v122, v2
	v_mov_b32_e32 v123, v2
	v_mov_b32_e32 v124, v2
	v_mov_b32_e32 v125, v2
	v_mov_b32_e32 v126, v2
	v_mov_b32_e32 v127, v2
	v_mov_b32_e32 v128, v2
	v_mov_b32_e32 v129, v2
	v_add_u32_e32 v151, 0xc000, v145
	v_add_u32_e32 v150, 0xe000, v145
	v_add_u32_e32 v152, 0x2000, v145
	v_add_u32_e32 v153, 0x4000, v145
	v_add_u32_e32 v154, 0x6000, v145
	v_add_u32_e32 v155, 0x8000, v145
	v_add_u32_e32 v156, 0xa000, v145
	v_add_u32_e32 v157, 0x2000, v146
	v_add_u32_e32 v158, 0x2000, v147
	v_add_u32_e32 v159, 0x2000, v148
	v_add_u32_e32 v160, 0x2000, v149
	s_barrier
	s_barrier

; #define GAS __attribute__((address_space(1)))
; __device__ __forceinline__ int otid() { int t = threadIdx.x; asm volatile("" : "+v"(t)); return t; }
; #define STAGE(P, GP, ktrel) do { const GAS char* _g = (GP) + (ktrel) * (BK * 2); \
;     __builtin_amdgcn_global_load_lds((const GAS unsigned*)(_g + so0), (unsigned*)((char*)(P) + tid_ * 16), 16, 0, 0); \
;     __builtin_amdgcn_global_load_lds((const GAS unsigned*)(_g + so1), (unsigned*)((char*)(P) + tid_ * 16 + 8192), 16, 0, 0); } while (0)
; template <int K, int LD = K>
; __device__ __forceinline__ void gemm_prefetch(const GAS bf16* A, const GAS bf16* Bt, int brow, int bcol) {
;   bf16* shm = (bf16*)smem_raw;
;   const int tid_ = otid();
;   unsigned so0, so1;
;   { int r_, c_; stage_rc(tid_ * 16, r_, c_); so0 = (unsigned)(r_ * LD + c_) * 2u; stage_rc(tid_ * 16 + 8192, r_, c_); so1 = (unsigned)(r_ * LD + c_) * 2u; }
;   const GAS char* pA0 = (const GAS char*)A + (long)brow * LD * 2; const GAS char* pA1 = pA0 + (long)HALF * LD * 2;
;   const GAS char* pB0 = (const GAS char*)Bt + (long)bcol * LD * 2; const GAS char* pB1 = pB0 + (long)HALF * LD * 2;
;   asm volatile("" : "+s"(pA0), "+s"(pA1), "+s"(pB0), "+s"(pB1));
;   STAGE(SB(0, 0), pB0, 0); STAGE(SA(0, 0), pA0, 0);
;   STAGE(SB(0, 1), pB1, 0); STAGE(SA(0, 1), pA1, 0);
;   STAGE(SB(1, 0), pB0, 1); STAGE(SA(1, 0), pA0, 1); STAGE(SB(1, 1), pB1, 1);
; }
; __device__ __forceinline__ void load_rr(const GAS float* ssq, int brow, int par) {
;   float* rr = (float*)(smem_raw + LDS_RR) + par * 256;
;   const int tx = otid();
;   if (tx < 256) {
;     const GAS f32x4* s = (const GAS f32x4*)(ssq + (size_t)(brow + tx) * 16);
;     f32x4 a = s[0], b = s[1], c = s[2], d = s[3];
;     float t = ((a.x + a.y) + (a.z + a.w)) + ((b.x + b.y) + (b.z + b.w)) + ((c.x + c.y) + (c.z + c.w)) + ((d.x + d.y) + (d.z + d.w));
.LBB0_92:
	s_or_b64 exec, exec, s[14:15]
	v_readfirstlane_b32 s14, v171
	s_add_i32 s3, s14, s3
	s_cmpk_gt_i32 s3, 0x57f
	s_cselect_b64 s[14:15], -1, 0
	s_and_b64 vcc, exec, s[14:15]
	s_mov_b32 s22, s41
	s_cbranch_vccnz .LBB0_85
	v_mov_b32_e32 v130, v170
	s_mul_hi_i32 s17, s3, 0x2e8ba2e9
	v_ashrrev_i32_e32 v132, 31, v130
	v_lshrrev_b32_e32 v132, 26, v132
	v_lshlrev_b32_e32 v148, 4, v130
	v_add_u32_e32 v132, v130, v132
	v_bfe_i32 v130, v130, 27, 1
	v_lshrrev_b32_e32 v130, 22, v130
	v_add_u32_e32 v130, v148, v130
	v_and_b32_e32 v130, 0xfffffc00, v130
	v_sub_u32_e32 v130, v148, v130
	v_lshrrev_b32_e32 v133, 4, v130
	v_bitop3_b32 v133, v133, v130, 32 bitop3:0x6c
	v_ashrrev_i32_e32 v130, 31, v130
	v_lshrrev_b32_e32 v130, 26, v130
	v_add_u32_e32 v130, v133, v130
	v_ashrrev_i32_e32 v130, 6, v130
	v_ashrrev_i32_e32 v132, 6, v132
	v_mul_i32_i24_e32 v137, 64, v130
	v_lshlrev_b32_e32 v136, 3, v132
	v_lshlrev_b32_e32 v132, 5, v132
	v_sub_u32_e32 v133, v133, v137
	s_lshr_b32 s18, s17, 31
	s_ashr_i32 s17, s17, 5
	v_and_b32_e32 v136, 0x1ffff0, v136
	v_and_b32_e32 v132, 32, v132
	v_ashrrev_i16_sdwa v133, v134, sext(v133) dst_sel:DWORD dst_unused:UNUSED_PAD src0_sel:DWORD src1_sel:BYTE_0
	s_add_i32 s17, s17, s18
	v_add_u32_sdwa v132, v132, sext(v133) dst_sel:DWORD dst_unused:UNUSED_PAD src0_sel:DWORD src1_sel:WORD_0
	v_add_lshl_u32 v130, v130, v136, 11
	s_mul_i32 s18, s17, 0xb0
	v_lshl_add_u32 v130, v132, 1, v130
	v_add_u32_e32 v132, 0x2000, v148
	s_sub_i32 s18, s3, s18
	v_ashrrev_i32_e32 v133, 31, v132
	s_lshl_b32 s17, s17, 3
	s_and_b32 s19, s18, 7
	v_lshrrev_b32_e32 v133, 22, v133
	s_or_b32 s28, s19, s17
	v_add_u32_e32 v133, v132, v133
	s_ashr_i32 s22, s18, 3
	s_lshl_b32 s18, s28, 8
	v_ashrrev_i32_e32 v133, 10, v133
	v_mul_i32_i24_e32 v136, 0x400, v133
	s_ashr_i32 s19, s18, 31
	s_lshl_b32 s20, s22, 8
	v_sub_u32_e32 v132, v132, v136
	s_lshl_b64 s[24:25], s[18:19], 11
	v_lshrrev_b32_e32 v136, 4, v132
	s_add_u32 s24, s26, s24
	v_bitop3_b32 v132, v136, v132, 32 bitop3:0x6c
	s_addc_u32 s25, s27, s25
	v_ashrrev_i32_e32 v137, 31, v132
	s_add_u32 s42, s24, 0x40000
	v_lshrrev_b32_e32 v137, 26, v137
	s_addc_u32 s43, s25, 0
	s_ashr_i32 s21, s20, 31
	v_add_u32_e32 v137, v132, v137
	s_lshl_b64 s[20:21], s[20:21], 11
	v_lshrrev_b32_e32 v138, 6, v137
	v_and_b32_e32 v137, 0xc0, v137
	s_add_u32 s20, s4, s20
	v_lshlrev_b32_e32 v136, 3, v133
	v_lshlrev_b32_e32 v133, 5, v133
	v_sub_u32_e32 v132, v132, v137
	s_addc_u32 s21, s5, s21
	v_add_u32_e32 v140, s29, v148
	v_and_b32_e32 v136, 0x1ffff0, v136
	v_and_b32_e32 v133, 32, v133
	v_ashrrev_i16_sdwa v132, v134, sext(v132) dst_sel:DWORD dst_unused:UNUSED_PAD src0_sel:DWORD src1_sel:BYTE_0
	s_add_u32 s44, s20, 0x40000
	v_readfirstlane_b32 s17, v140
	v_add_u32_e32 v140, 0x2000, v140
	v_add_u32_sdwa v132, v133, sext(v132) dst_sel:DWORD dst_unused:UNUSED_PAD src0_sel:DWORD src1_sel:WORD_0
	v_add_lshl_u32 v133, v138, v136, 11
	s_addc_u32 s45, s21, 0
	s_mov_b32 m0, s17
	v_readfirstlane_b32 s17, v140
	v_add_u32_e32 v149, 0x100, v148
	v_lshl_add_u32 v132, v132, 1, v133
	v_add_u32_e32 v144, 0x2000, v149
	s_mov_b32 m0, s17
	v_readfirstlane_b32 s17, v149
	v_mov_b32_e32 v133, v131
	s_mov_b32 m0, s17
	v_readfirstlane_b32 s17, v144
	v_add_u32_e32 v150, s30, v148
	v_lshl_add_u64 v[138:139], s[20:21], 0, v[132:133]
	v_lshl_add_u64 v[142:143], s[24:25], 0, v[132:133]
	s_mov_b32 m0, s17
	v_readfirstlane_b32 s17, v150
	v_lshl_add_u64 v[146:147], s[44:45], 0, v[132:133]
	v_add_u32_e32 v133, 0x2000, v150
	s_mov_b32 m0, s17
	v_readfirstlane_b32 s17, v133
	v_add_u32_e32 v133, 0x4000, v149
	s_mov_b32 m0, s17
	v_readfirstlane_b32 s17, v133
	s_mov_b32 m0, s17
	v_lshl_add_u64 v[136:137], s[20:21], 0, v[130:131]
	v_lshl_add_u64 v[140:141], s[24:25], 0, v[130:131]
	v_lshl_add_u64 v[144:145], s[44:45], 0, v[130:131]
	v_add_u32_e32 v130, 0x6000, v149
	s_nop 0
	v_readfirstlane_b32 s17, v130
	v_add_u32_e32 v130, s31, v148
	s_mov_b32 m0, s17
	v_readfirstlane_b32 s17, v130
	v_add_u32_e32 v130, 0x2000, v130
	v_cmp_gt_i32_e32 vcc, s34, v170
	s_and_saveexec_b64 s[98:99], vcc
	v_add_u32_e32 v204, s18, v170
	v_ashrrev_i32_e32 v205, 31, v204
	v_lshlrev_b64 v[204:205], 6, v[204:205]
	v_lshl_add_u64 v[204:205], s[6:7], 0, v[204:205]
	global_load_dwordx4 v[188:191], v[204:205], off
	global_load_dwordx4 v[192:195], v[204:205], off offset:16
	global_load_dwordx4 v[196:199], v[204:205], off offset:32
	global_load_dwordx4 v[200:203], v[204:205], off offset:48
	s_or_b64 exec, exec, s[98:99]
	v_lshl_add_u64 v[132:133], v[136:137], 0, s[8:9]
	s_mov_b32 m0, s17
	v_readfirstlane_b32 s17, v130
	v_add_u32_e32 v130, 0x8000, v149
	global_load_lds_dwordx4 v[132:133], off
	v_lshl_add_u64 v[132:133], v[138:139], 0, s[8:9]
	s_mov_b32 m0, s17
	v_readfirstlane_b32 s17, v130
	v_add_u32_e32 v130, 0xa000, v149
	global_load_lds_dwordx4 v[132:133], off
	v_lshl_add_u64 v[132:133], v[140:141], 0, s[8:9]
	s_mov_b32 m0, s17
	v_readfirstlane_b32 s17, v130
	v_add_u32_e32 v130, s33, v148
	global_load_lds_dwordx4 v[132:133], off
	v_lshl_add_u64 v[132:133], v[142:143], 0, s[8:9]
	s_mov_b32 m0, s17
	v_readfirstlane_b32 s17, v130
	v_add_u32_e32 v130, 0x2000, v130
	global_load_lds_dwordx4 v[132:133], off
	v_lshl_add_u64 v[132:133], v[144:145], 0, s[8:9]
	s_mov_b32 m0, s17
	v_readfirstlane_b32 s17, v130
	global_load_lds_dwordx4 v[132:133], off
	v_lshl_add_u64 v[132:133], v[146:147], 0, s[8:9]
	s_mov_b32 m0, s17
	v_mov_b32_e32 v130, v170
	global_load_lds_dwordx4 v[132:133], off
	s_nop 0
	v_cmp_gt_i32_e32 vcc, s34, v130
	s_and_saveexec_b64 s[20:21], vcc
	s_cbranch_execz .LBB0_84
	v_add_u32_e32 v132, s18, v130
	v_ashrrev_i32_e32 v133, 31, v132
	v_lshlrev_b64 v[132:133], 6, v[132:133]
	v_lshl_add_u64 v[132:133], s[6:7], 0, v[132:133]
	s_branch .LBB0_84

; #define GAS __attribute__((address_space(1)))
; __device__ __forceinline__ unsigned f2bf(float f) { return pk2(f, f) & 0xffffu; }
; __device__ __forceinline__ float sigmoidf_(float v) { return __builtin_amdgcn_rcpf(1.f + __builtin_amdgcn_exp2f(-LOG2E * v)); }
; __device__ __forceinline__ void phase_up(int pass) {
;     ...
;     EPI_IDS
;     const float* rr = (const float*)(smem_raw + LDS_RR) + par * 256;
;     GAS char* tb = (GAS char*)act + ((size_t)brow * FFP + (bcol >> 1)) * 2;
;     const unsigned off0 = (unsigned)((wr * 64 + fq * 4) * FFP + wc * 16 + fr) * 2u;
; #pragma unroll
;     for (int ai = 0; ai < 2; ++ai)
; #pragma unroll
;       for (int m = 0; m < 4; ++m)
; #pragma unroll
;         for (int j = 0; j < 4; ++j) {
;           const int rowl = ai * 128 + wr * 64 + m * 16 + fq * 4 + j;
;           const float r = rr[rowl];
; #pragma unroll
;           for (int bj = 0; bj < 2; ++bj) {
;             const float g = acc[ai][bj][m][0][j] * r, u = acc[ai][bj][m][1][j] * r;
;             const float v = g * sigmoidf_(g) * u;
;             *(GAS unsigned short*)(tb + (off0 + (unsigned)(((ai * 128 + m * 16 + j) * FFP + bj * 64) * 2))) = (unsigned short)f2bf(v);
;           }
;         }
.LBB0_880:
	v_and_b32_e32 v174, 15, v170
	v_lshrrev_b32_e32 v175, 8, v170
	v_lshl_or_b32 v175, v175, 6, v174
	v_bfe_u32 v176, v170, 4, 2
	v_bfe_u32 v177, v170, 6, 2
	v_lshlrev_b32_e32 v176, 2, v176
	v_lshl_or_b32 v176, v177, 4, v176
	v_mul_u32_u24_e32 v186, 0xb40, v175
	v_add_lshl_u32 v186, v186, v176, 1
	s_lshl_b32 s16, s37, 10
	s_add_i32 s16, s16, 0x20100
	v_lshl_add_u32 v174, v175, 2, s16
	ds_read_b32 v178, v174
	ds_read_b32 v179, v174 offset:64
	ds_read_b32 v180, v174 offset:128
	ds_read_b32 v181, v174 offset:192
	ds_read_b32 v182, v174 offset:512
	ds_read_b32 v183, v174 offset:576
	ds_read_b32 v184, v174 offset:640
	ds_read_b32 v185, v174 offset:704
	s_lshl_b32 s17, s41, 7
	s_mul_hi_i32 s15, s14, 0xb40
	s_mulk_i32 s14, 0xb40
	s_ashr_i32 s18, s17, 31
	s_add_u32 s14, s14, s17
	s_addc_u32 s15, s15, s18
	s_lshl_b64 s[14:15], s[14:15], 1
	s_add_u32 s14, s35, s14
	s_addc_u32 s15, s36, s15
	s_waitcnt lgkmcnt(0)
	v_mul_f32_e32 v118, v118, v178
	v_mul_f32_e32 v119, v119, v178
	v_mul_f32_e32 v120, v120, v178
	v_mul_f32_e32 v121, v121, v178
	v_mul_f32_e32 v174, 0xbfb8aa3b, v118
	v_mul_f32_e32 v175, 0xbfb8aa3b, v119
	v_mul_f32_e32 v176, 0xbfb8aa3b, v120
	v_mul_f32_e32 v177, 0xbfb8aa3b, v121
	v_exp_f32_e32 v174, v174
	v_exp_f32_e32 v175, v175
	v_exp_f32_e32 v176, v176
	v_exp_f32_e32 v177, v177
	v_mul_f32_e32 v114, v114, v178
	v_mul_f32_e32 v115, v115, v178
	v_mul_f32_e32 v116, v116, v178
	v_mul_f32_e32 v117, v117, v178
	v_add_f32_e32 v174, 1.0, v174
	v_add_f32_e32 v175, 1.0, v175
	v_add_f32_e32 v176, 1.0, v176
	v_add_f32_e32 v177, 1.0, v177
	v_rcp_f32_e32 v174, v174
	v_rcp_f32_e32 v175, v175
	v_rcp_f32_e32 v176, v176
	v_rcp_f32_e32 v177, v177
	v_mul_f32_e32 v118, v118, v174
	v_mul_f32_e32 v119, v119, v175
	v_mul_f32_e32 v120, v120, v176
	v_mul_f32_e32 v121, v121, v177
	v_mul_f32_e32 v114, v114, v118
	v_mul_f32_e32 v115, v115, v119
	v_mul_f32_e32 v116, v116, v120
	v_mul_f32_e32 v117, v117, v121
	v_cvt_pk_bf16_f32 v114, v114, v115
	v_cvt_pk_bf16_f32 v115, v116, v117
	global_store_dwordx2 v186, v[114:115], s[14:15]
	v_mul_f32_e32 v126, v126, v178
	v_mul_f32_e32 v127, v127, v178
	v_mul_f32_e32 v128, v128, v178
	v_mul_f32_e32 v129, v129, v178
	v_mul_f32_e32 v174, 0xbfb8aa3b, v126
	v_mul_f32_e32 v175, 0xbfb8aa3b, v127
	v_mul_f32_e32 v176, 0xbfb8aa3b, v128
	v_mul_f32_e32 v177, 0xbfb8aa3b, v129
	v_exp_f32_e32 v174, v174
	v_exp_f32_e32 v175, v175
	v_exp_f32_e32 v176, v176
	v_exp_f32_e32 v177, v177
	v_mul_f32_e32 v122, v122, v178
	v_mul_f32_e32 v123, v123, v178
	v_mul_f32_e32 v124, v124, v178
	v_mul_f32_e32 v125, v125, v178
	v_add_f32_e32 v174, 1.0, v174
	v_add_f32_e32 v175, 1.0, v175
	v_add_f32_e32 v176, 1.0, v176
	v_add_f32_e32 v177, 1.0, v177
	v_rcp_f32_e32 v174, v174
	v_rcp_f32_e32 v175, v175
	v_rcp_f32_e32 v176, v176
	v_rcp_f32_e32 v177, v177
	v_mul_f32_e32 v126, v126, v174
	v_mul_f32_e32 v127, v127, v175
	v_mul_f32_e32 v128, v128, v176
	v_mul_f32_e32 v129, v129, v177
	v_mul_f32_e32 v122, v122, v126
	v_mul_f32_e32 v123, v123, v127
	v_mul_f32_e32 v124, v124, v128
	v_mul_f32_e32 v125, v125, v129
	v_cvt_pk_bf16_f32 v122, v122, v123
	v_cvt_pk_bf16_f32 v123, v124, v125
	global_store_dwordx2 v186, v[122:123], s[14:15] offset:128
	s_add_u32 s14, s14, 0x16800
	s_addc_u32 s15, s15, 0
	v_mul_f32_e32 v102, v102, v179
	v_mul_f32_e32 v103, v103, v179
	v_mul_f32_e32 v104, v104, v179
	v_mul_f32_e32 v105, v105, v179
	v_mul_f32_e32 v174, 0xbfb8aa3b, v102
	v_mul_f32_e32 v175, 0xbfb8aa3b, v103
	v_mul_f32_e32 v176, 0xbfb8aa3b, v104
	v_mul_f32_e32 v177, 0xbfb8aa3b, v105
	v_exp_f32_e32 v174, v174
	v_exp_f32_e32 v175, v175
	v_exp_f32_e32 v176, v176
	v_exp_f32_e32 v177, v177
	v_mul_f32_e32 v98, v98, v179
	v_mul_f32_e32 v99, v99, v179
	v_mul_f32_e32 v100, v100, v179
	v_mul_f32_e32 v101, v101, v179
	v_add_f32_e32 v174, 1.0, v174
	v_add_f32_e32 v175, 1.0, v175
	v_add_f32_e32 v176, 1.0, v176
	v_add_f32_e32 v177, 1.0, v177
	v_rcp_f32_e32 v174, v174
	v_rcp_f32_e32 v175, v175
	v_rcp_f32_e32 v176, v176
	v_rcp_f32_e32 v177, v177
	v_mul_f32_e32 v102, v102, v174
	v_mul_f32_e32 v103, v103, v175
	v_mul_f32_e32 v104, v104, v176
	v_mul_f32_e32 v105, v105, v177
	v_mul_f32_e32 v98, v98, v102
	v_mul_f32_e32 v99, v99, v103
	v_mul_f32_e32 v100, v100, v104
	v_mul_f32_e32 v101, v101, v105
	v_cvt_pk_bf16_f32 v98, v98, v99
	v_cvt_pk_bf16_f32 v99, v100, v101
	global_store_dwordx2 v186, v[98:99], s[14:15]
	v_mul_f32_e32 v110, v110, v179
	v_mul_f32_e32 v111, v111, v179
	v_mul_f32_e32 v112, v112, v179
	v_mul_f32_e32 v113, v113, v179
	v_mul_f32_e32 v174, 0xbfb8aa3b, v110
	v_mul_f32_e32 v175, 0xbfb8aa3b, v111
	v_mul_f32_e32 v176, 0xbfb8aa3b, v112
	v_mul_f32_e32 v177, 0xbfb8aa3b, v113
	v_exp_f32_e32 v174, v174
	v_exp_f32_e32 v175, v175
	v_exp_f32_e32 v176, v176
	v_exp_f32_e32 v177, v177
	v_mul_f32_e32 v106, v106, v179
	v_mul_f32_e32 v107, v107, v179
	v_mul_f32_e32 v108, v108, v179
	v_mul_f32_e32 v109, v109, v179
	v_add_f32_e32 v174, 1.0, v174
	v_add_f32_e32 v175, 1.0, v175
	v_add_f32_e32 v176, 1.0, v176
	v_add_f32_e32 v177, 1.0, v177
	v_rcp_f32_e32 v174, v174
	v_rcp_f32_e32 v175, v175
	v_rcp_f32_e32 v176, v176
	v_rcp_f32_e32 v177, v177
	v_mul_f32_e32 v110, v110, v174
	v_mul_f32_e32 v111, v111, v175
	v_mul_f32_e32 v112, v112, v176
	v_mul_f32_e32 v113, v113, v177
	v_mul_f32_e32 v106, v106, v110
	v_mul_f32_e32 v107, v107, v111
	v_mul_f32_e32 v108, v108, v112
	v_mul_f32_e32 v109, v109, v113
	v_cvt_pk_bf16_f32 v106, v106, v107
	v_cvt_pk_bf16_f32 v107, v108, v109
	global_store_dwordx2 v186, v[106:107], s[14:15] offset:128
	s_add_u32 s14, s14, 0x16800
	s_addc_u32 s15, s15, 0
	v_mul_f32_e32 v86, v86, v180
	v_mul_f32_e32 v87, v87, v180
	v_mul_f32_e32 v88, v88, v180
	v_mul_f32_e32 v89, v89, v180
; #define GAS __attribute__((address_space(1)))
; __device__ __forceinline__ unsigned f2bf(float f) { return pk2(f, f) & 0xffffu; }
; __device__ __forceinline__ float sigmoidf_(float v) { return __builtin_amdgcn_rcpf(1.f + __builtin_amdgcn_exp2f(-LOG2E * v)); }
; __device__ __forceinline__ void phase_up(int pass) {
;     ...
; #pragma unroll
;     for (int ai = 0; ai < 2; ++ai)
; #pragma unroll
;       for (int m = 0; m < 4; ++m)
; #pragma unroll
;         for (int j = 0; j < 4; ++j) {
;           const int rowl = ai * 128 + wr * 64 + m * 16 + fq * 4 + j;
;           const float r = rr[rowl];
; #pragma unroll
;           for (int bj = 0; bj < 2; ++bj) {
;             const float g = acc[ai][bj][m][0][j] * r, u = acc[ai][bj][m][1][j] * r;
;             const float v = g * sigmoidf_(g) * u;
;             *(GAS unsigned short*)(tb + (off0 + (unsigned)(((ai * 128 + m * 16 + j) * FFP + bj * 64) * 2))) = (unsigned short)f2bf(v);
;           }
;         }
	v_mul_f32_e32 v174, 0xbfb8aa3b, v86
	v_mul_f32_e32 v175, 0xbfb8aa3b, v87
	v_mul_f32_e32 v176, 0xbfb8aa3b, v88
	v_mul_f32_e32 v177, 0xbfb8aa3b, v89
	v_exp_f32_e32 v174, v174
	v_exp_f32_e32 v175, v175
	v_exp_f32_e32 v176, v176
	v_exp_f32_e32 v177, v177
	v_mul_f32_e32 v82, v82, v180
	v_mul_f32_e32 v83, v83, v180
	v_mul_f32_e32 v84, v84, v180
	v_mul_f32_e32 v85, v85, v180
	v_add_f32_e32 v174, 1.0, v174
	v_add_f32_e32 v175, 1.0, v175
	v_add_f32_e32 v176, 1.0, v176
	v_add_f32_e32 v177, 1.0, v177
	v_rcp_f32_e32 v174, v174
	v_rcp_f32_e32 v175, v175
	v_rcp_f32_e32 v176, v176
	v_rcp_f32_e32 v177, v177
	v_mul_f32_e32 v86, v86, v174
	v_mul_f32_e32 v87, v87, v175
	v_mul_f32_e32 v88, v88, v176
	v_mul_f32_e32 v89, v89, v177
	v_mul_f32_e32 v82, v82, v86
	v_mul_f32_e32 v83, v83, v87
	v_mul_f32_e32 v84, v84, v88
	v_mul_f32_e32 v85, v85, v89
	v_cvt_pk_bf16_f32 v82, v82, v83
	v_cvt_pk_bf16_f32 v83, v84, v85
	global_store_dwordx2 v186, v[82:83], s[14:15]
	v_mul_f32_e32 v94, v94, v180
	v_mul_f32_e32 v95, v95, v180
	v_mul_f32_e32 v96, v96, v180
	v_mul_f32_e32 v97, v97, v180
	v_mul_f32_e32 v174, 0xbfb8aa3b, v94
	v_mul_f32_e32 v175, 0xbfb8aa3b, v95
	v_mul_f32_e32 v176, 0xbfb8aa3b, v96
	v_mul_f32_e32 v177, 0xbfb8aa3b, v97
	v_exp_f32_e32 v174, v174
	v_exp_f32_e32 v175, v175
	v_exp_f32_e32 v176, v176
	v_exp_f32_e32 v177, v177
	v_mul_f32_e32 v90, v90, v180
	v_mul_f32_e32 v91, v91, v180
	v_mul_f32_e32 v92, v92, v180
	v_mul_f32_e32 v93, v93, v180
	v_add_f32_e32 v174, 1.0, v174
	v_add_f32_e32 v175, 1.0, v175
	v_add_f32_e32 v176, 1.0, v176
	v_add_f32_e32 v177, 1.0, v177
	v_rcp_f32_e32 v174, v174
	v_rcp_f32_e32 v175, v175
	v_rcp_f32_e32 v176, v176
	v_rcp_f32_e32 v177, v177
	v_mul_f32_e32 v94, v94, v174
	v_mul_f32_e32 v95, v95, v175
	v_mul_f32_e32 v96, v96, v176
	v_mul_f32_e32 v97, v97, v177
	v_mul_f32_e32 v90, v90, v94
	v_mul_f32_e32 v91, v91, v95
	v_mul_f32_e32 v92, v92, v96
	v_mul_f32_e32 v93, v93, v97
	v_cvt_pk_bf16_f32 v90, v90, v91
	v_cvt_pk_bf16_f32 v91, v92, v93
	global_store_dwordx2 v186, v[90:91], s[14:15] offset:128
	s_add_u32 s14, s14, 0x16800
	s_addc_u32 s15, s15, 0
	v_mul_f32_e32 v70, v70, v181
	v_mul_f32_e32 v71, v71, v181
	v_mul_f32_e32 v72, v72, v181
	v_mul_f32_e32 v73, v73, v181
	v_mul_f32_e32 v174, 0xbfb8aa3b, v70
	v_mul_f32_e32 v175, 0xbfb8aa3b, v71
	v_mul_f32_e32 v176, 0xbfb8aa3b, v72
	v_mul_f32_e32 v177, 0xbfb8aa3b, v73
	v_exp_f32_e32 v174, v174
	v_exp_f32_e32 v175, v175
	v_exp_f32_e32 v176, v176
	v_exp_f32_e32 v177, v177
	v_mul_f32_e32 v66, v66, v181
	v_mul_f32_e32 v67, v67, v181
	v_mul_f32_e32 v68, v68, v181
	v_mul_f32_e32 v69, v69, v181
	v_add_f32_e32 v174, 1.0, v174
	v_add_f32_e32 v175, 1.0, v175
	v_add_f32_e32 v176, 1.0, v176
	v_add_f32_e32 v177, 1.0, v177
	v_rcp_f32_e32 v174, v174
	v_rcp_f32_e32 v175, v175
	v_rcp_f32_e32 v176, v176
	v_rcp_f32_e32 v177, v177
	v_mul_f32_e32 v70, v70, v174
	v_mul_f32_e32 v71, v71, v175
	v_mul_f32_e32 v72, v72, v176
	v_mul_f32_e32 v73, v73, v177
	v_mul_f32_e32 v66, v66, v70
	v_mul_f32_e32 v67, v67, v71
	v_mul_f32_e32 v68, v68, v72
	v_mul_f32_e32 v69, v69, v73
	v_cvt_pk_bf16_f32 v66, v66, v67
	v_cvt_pk_bf16_f32 v67, v68, v69
	global_store_dwordx2 v186, v[66:67], s[14:15]
	v_mul_f32_e32 v78, v78, v181
	v_mul_f32_e32 v79, v79, v181
	v_mul_f32_e32 v80, v80, v181
	v_mul_f32_e32 v81, v81, v181
	v_mul_f32_e32 v174, 0xbfb8aa3b, v78
	v_mul_f32_e32 v175, 0xbfb8aa3b, v79
	v_mul_f32_e32 v176, 0xbfb8aa3b, v80
	v_mul_f32_e32 v177, 0xbfb8aa3b, v81
	v_exp_f32_e32 v174, v174
	v_exp_f32_e32 v175, v175
	v_exp_f32_e32 v176, v176
	v_exp_f32_e32 v177, v177
	v_mul_f32_e32 v74, v74, v181
	v_mul_f32_e32 v75, v75, v181
	v_mul_f32_e32 v76, v76, v181
	v_mul_f32_e32 v77, v77, v181
	v_add_f32_e32 v174, 1.0, v174
	v_add_f32_e32 v175, 1.0, v175
	v_add_f32_e32 v176, 1.0, v176
	v_add_f32_e32 v177, 1.0, v177
	v_rcp_f32_e32 v174, v174
	v_rcp_f32_e32 v175, v175
	v_rcp_f32_e32 v176, v176
	v_rcp_f32_e32 v177, v177
	v_mul_f32_e32 v78, v78, v174
	v_mul_f32_e32 v79, v79, v175
	v_mul_f32_e32 v80, v80, v176
	v_mul_f32_e32 v81, v81, v177
	v_mul_f32_e32 v74, v74, v78
	v_mul_f32_e32 v75, v75, v79
	v_mul_f32_e32 v76, v76, v80
	v_mul_f32_e32 v77, v77, v81
	v_cvt_pk_bf16_f32 v74, v74, v75
	v_cvt_pk_bf16_f32 v75, v76, v77
	global_store_dwordx2 v186, v[74:75], s[14:15] offset:128
	s_add_u32 s14, s14, 0x70800
	s_addc_u32 s15, s15, 0
	v_mul_f32_e32 v54, v54, v182
	v_mul_f32_e32 v55, v55, v182
	v_mul_f32_e32 v56, v56, v182
	v_mul_f32_e32 v57, v57, v182
	v_mul_f32_e32 v174, 0xbfb8aa3b, v54
	v_mul_f32_e32 v175, 0xbfb8aa3b, v55
	v_mul_f32_e32 v176, 0xbfb8aa3b, v56
	v_mul_f32_e32 v177, 0xbfb8aa3b, v57
	v_exp_f32_e32 v174, v174
	v_exp_f32_e32 v175, v175
	v_exp_f32_e32 v176, v176
	v_exp_f32_e32 v177, v177
	v_mul_f32_e32 v50, v50, v182
	v_mul_f32_e32 v51, v51, v182
	v_mul_f32_e32 v52, v52, v182
	v_mul_f32_e32 v53, v53, v182
	v_add_f32_e32 v174, 1.0, v174
	v_add_f32_e32 v175, 1.0, v175
	v_add_f32_e32 v176, 1.0, v176
	v_add_f32_e32 v177, 1.0, v177
	v_rcp_f32_e32 v174, v174
	v_rcp_f32_e32 v175, v175
	v_rcp_f32_e32 v176, v176
	v_rcp_f32_e32 v177, v177
	v_mul_f32_e32 v54, v54, v174
	v_mul_f32_e32 v55, v55, v175
	v_mul_f32_e32 v56, v56, v176
	v_mul_f32_e32 v57, v57, v177
	v_mul_f32_e32 v50, v50, v54
	v_mul_f32_e32 v51, v51, v55
	v_mul_f32_e32 v52, v52, v56
	v_mul_f32_e32 v53, v53, v57
	v_cvt_pk_bf16_f32 v50, v50, v51
	v_cvt_pk_bf16_f32 v51, v52, v53
	global_store_dwordx2 v186, v[50:51], s[14:15]
	v_mul_f32_e32 v62, v62, v182
	v_mul_f32_e32 v63, v63, v182
	v_mul_f32_e32 v64, v64, v182
	v_mul_f32_e32 v65, v65, v182
	v_mul_f32_e32 v174, 0xbfb8aa3b, v62
	v_mul_f32_e32 v175, 0xbfb8aa3b, v63
	v_mul_f32_e32 v176, 0xbfb8aa3b, v64
	v_mul_f32_e32 v177, 0xbfb8aa3b, v65
	v_exp_f32_e32 v174, v174
; #define GAS __attribute__((address_space(1)))
; __device__ __forceinline__ unsigned f2bf(float f) { return pk2(f, f) & 0xffffu; }
; __device__ __forceinline__ float sigmoidf_(float v) { return __builtin_amdgcn_rcpf(1.f + __builtin_amdgcn_exp2f(-LOG2E * v)); }
; __device__ __forceinline__ void phase_up(int pass) {
;     ...
; #pragma unroll
;     for (int ai = 0; ai < 2; ++ai)
; #pragma unroll
;       for (int m = 0; m < 4; ++m)
; #pragma unroll
;         for (int j = 0; j < 4; ++j) {
;           const int rowl = ai * 128 + wr * 64 + m * 16 + fq * 4 + j;
;           const float r = rr[rowl];
; #pragma unroll
;           for (int bj = 0; bj < 2; ++bj) {
;             const float g = acc[ai][bj][m][0][j] * r, u = acc[ai][bj][m][1][j] * r;
;             const float v = g * sigmoidf_(g) * u;
;             *(GAS unsigned short*)(tb + (off0 + (unsigned)(((ai * 128 + m * 16 + j) * FFP + bj * 64) * 2))) = (unsigned short)f2bf(v);
;           }
;         }
	v_exp_f32_e32 v175, v175
	v_exp_f32_e32 v176, v176
	v_exp_f32_e32 v177, v177
	v_mul_f32_e32 v58, v58, v182
	v_mul_f32_e32 v59, v59, v182
	v_mul_f32_e32 v60, v60, v182
	v_mul_f32_e32 v61, v61, v182
	v_add_f32_e32 v174, 1.0, v174
	v_add_f32_e32 v175, 1.0, v175
	v_add_f32_e32 v176, 1.0, v176
	v_add_f32_e32 v177, 1.0, v177
	v_rcp_f32_e32 v174, v174
	v_rcp_f32_e32 v175, v175
	v_rcp_f32_e32 v176, v176
	v_rcp_f32_e32 v177, v177
	v_mul_f32_e32 v62, v62, v174
	v_mul_f32_e32 v63, v63, v175
	v_mul_f32_e32 v64, v64, v176
	v_mul_f32_e32 v65, v65, v177
	v_mul_f32_e32 v58, v58, v62
	v_mul_f32_e32 v59, v59, v63
	v_mul_f32_e32 v60, v60, v64
	v_mul_f32_e32 v61, v61, v65
	v_cvt_pk_bf16_f32 v58, v58, v59
	v_cvt_pk_bf16_f32 v59, v60, v61
	global_store_dwordx2 v186, v[58:59], s[14:15] offset:128
	s_add_u32 s14, s14, 0x16800
	s_addc_u32 s15, s15, 0
	v_mul_f32_e32 v42, v42, v183
	v_mul_f32_e32 v43, v43, v183
	v_mul_f32_e32 v44, v44, v183
	v_mul_f32_e32 v45, v45, v183
	v_mul_f32_e32 v174, 0xbfb8aa3b, v42
	v_mul_f32_e32 v175, 0xbfb8aa3b, v43
	v_mul_f32_e32 v176, 0xbfb8aa3b, v44
	v_mul_f32_e32 v177, 0xbfb8aa3b, v45
	v_exp_f32_e32 v174, v174
	v_exp_f32_e32 v175, v175
	v_exp_f32_e32 v176, v176
	v_exp_f32_e32 v177, v177
	v_mul_f32_e32 v34, v34, v183
	v_mul_f32_e32 v35, v35, v183
	v_mul_f32_e32 v36, v36, v183
	v_mul_f32_e32 v37, v37, v183
	v_add_f32_e32 v174, 1.0, v174
	v_add_f32_e32 v175, 1.0, v175
	v_add_f32_e32 v176, 1.0, v176
	v_add_f32_e32 v177, 1.0, v177
	v_rcp_f32_e32 v174, v174
	v_rcp_f32_e32 v175, v175
	v_rcp_f32_e32 v176, v176
	v_rcp_f32_e32 v177, v177
	v_mul_f32_e32 v42, v42, v174
	v_mul_f32_e32 v43, v43, v175
	v_mul_f32_e32 v44, v44, v176
	v_mul_f32_e32 v45, v45, v177
	v_mul_f32_e32 v34, v34, v42
	v_mul_f32_e32 v35, v35, v43
	v_mul_f32_e32 v36, v36, v44
	v_mul_f32_e32 v37, v37, v45
	v_cvt_pk_bf16_f32 v34, v34, v35
	v_cvt_pk_bf16_f32 v35, v36, v37
	global_store_dwordx2 v186, v[34:35], s[14:15]
	v_mul_f32_e32 v46, v46, v183
	v_mul_f32_e32 v47, v47, v183
	v_mul_f32_e32 v48, v48, v183
	v_mul_f32_e32 v49, v49, v183
	v_mul_f32_e32 v174, 0xbfb8aa3b, v46
	v_mul_f32_e32 v175, 0xbfb8aa3b, v47
	v_mul_f32_e32 v176, 0xbfb8aa3b, v48
	v_mul_f32_e32 v177, 0xbfb8aa3b, v49
	v_exp_f32_e32 v174, v174
	v_exp_f32_e32 v175, v175
	v_exp_f32_e32 v176, v176
	v_exp_f32_e32 v177, v177
	v_mul_f32_e32 v38, v38, v183
	v_mul_f32_e32 v39, v39, v183
	v_mul_f32_e32 v40, v40, v183
	v_mul_f32_e32 v41, v41, v183
	v_add_f32_e32 v174, 1.0, v174
	v_add_f32_e32 v175, 1.0, v175
	v_add_f32_e32 v176, 1.0, v176
	v_add_f32_e32 v177, 1.0, v177
	v_rcp_f32_e32 v174, v174
	v_rcp_f32_e32 v175, v175
	v_rcp_f32_e32 v176, v176
	v_rcp_f32_e32 v177, v177
	v_mul_f32_e32 v46, v46, v174
	v_mul_f32_e32 v47, v47, v175
	v_mul_f32_e32 v48, v48, v176
	v_mul_f32_e32 v49, v49, v177
	v_mul_f32_e32 v38, v38, v46
	v_mul_f32_e32 v39, v39, v47
	v_mul_f32_e32 v40, v40, v48
	v_mul_f32_e32 v41, v41, v49
	v_cvt_pk_bf16_f32 v38, v38, v39
	v_cvt_pk_bf16_f32 v39, v40, v41
	global_store_dwordx2 v186, v[38:39], s[14:15] offset:128
	s_add_u32 s14, s14, 0x16800
	s_addc_u32 s15, s15, 0
	v_mul_f32_e32 v22, v22, v184
	v_mul_f32_e32 v23, v23, v184
	v_mul_f32_e32 v24, v24, v184
	v_mul_f32_e32 v25, v25, v184
	v_mul_f32_e32 v174, 0xbfb8aa3b, v22
	v_mul_f32_e32 v175, 0xbfb8aa3b, v23
	v_mul_f32_e32 v176, 0xbfb8aa3b, v24
	v_mul_f32_e32 v177, 0xbfb8aa3b, v25
	v_exp_f32_e32 v174, v174
	v_exp_f32_e32 v175, v175
	v_exp_f32_e32 v176, v176
	v_exp_f32_e32 v177, v177
	v_mul_f32_e32 v18, v18, v184
	v_mul_f32_e32 v19, v19, v184
	v_mul_f32_e32 v20, v20, v184
	v_mul_f32_e32 v21, v21, v184
	v_add_f32_e32 v174, 1.0, v174
	v_add_f32_e32 v175, 1.0, v175
	v_add_f32_e32 v176, 1.0, v176
	v_add_f32_e32 v177, 1.0, v177
	v_rcp_f32_e32 v174, v174
	v_rcp_f32_e32 v175, v175
	v_rcp_f32_e32 v176, v176
	v_rcp_f32_e32 v177, v177
	v_mul_f32_e32 v22, v22, v174
	v_mul_f32_e32 v23, v23, v175
	v_mul_f32_e32 v24, v24, v176
	v_mul_f32_e32 v25, v25, v177
	v_mul_f32_e32 v18, v18, v22
	v_mul_f32_e32 v19, v19, v23
	v_mul_f32_e32 v20, v20, v24
	v_mul_f32_e32 v21, v21, v25
	v_cvt_pk_bf16_f32 v18, v18, v19
	v_cvt_pk_bf16_f32 v19, v20, v21
	global_store_dwordx2 v186, v[18:19], s[14:15]
	v_mul_f32_e32 v30, v30, v184
	v_mul_f32_e32 v31, v31, v184
	v_mul_f32_e32 v32, v32, v184
	v_mul_f32_e32 v33, v33, v184
	v_mul_f32_e32 v174, 0xbfb8aa3b, v30
	v_mul_f32_e32 v175, 0xbfb8aa3b, v31
	v_mul_f32_e32 v176, 0xbfb8aa3b, v32
	v_mul_f32_e32 v177, 0xbfb8aa3b, v33
; #define GAS __attribute__((address_space(1)))
; __device__ __forceinline__ unsigned f2bf(float f) { return pk2(f, f) & 0xffffu; }
; __device__ __forceinline__ float sigmoidf_(float v) { return __builtin_amdgcn_rcpf(1.f + __builtin_amdgcn_exp2f(-LOG2E * v)); }
; __device__ __forceinline__ void load_rr(const GAS float* ssq, int brow, int par) {
;     ...
;   if (tx < 256) {
;     const GAS f32x4* s = (const GAS f32x4*)(ssq + (size_t)(brow + tx) * 16);
;     f32x4 a = s[0], b = s[1], c = s[2], d = s[3];
;     float t = ((a.x + a.y) + (a.z + a.w)) + ((b.x + b.y) + (b.z + b.w)) + ((c.x + c.y) + (c.z + c.w)) + ((d.x + d.y) + (d.z + d.w));
;     rr[tx] = rsqrtf(t * (1.f / DM) + EPS);
;   }
; __device__ __forceinline__ void phase_up(int pass) {
;     ...
; #pragma unroll
;     for (int ai = 0; ai < 2; ++ai)
; #pragma unroll
;       for (int m = 0; m < 4; ++m)
; #pragma unroll
;         for (int j = 0; j < 4; ++j) {
;           const int rowl = ai * 128 + wr * 64 + m * 16 + fq * 4 + j;
;           const float r = rr[rowl];
; #pragma unroll
;           for (int bj = 0; bj < 2; ++bj) {
;             const float g = acc[ai][bj][m][0][j] * r, u = acc[ai][bj][m][1][j] * r;
;             const float v = g * sigmoidf_(g) * u;
;             *(GAS unsigned short*)(tb + (off0 + (unsigned)(((ai * 128 + m * 16 + j) * FFP + bj * 64) * 2))) = (unsigned short)f2bf(v);
;           }
;         }
	v_exp_f32_e32 v174, v174
	v_exp_f32_e32 v175, v175
	v_exp_f32_e32 v176, v176
	v_exp_f32_e32 v177, v177
	v_mul_f32_e32 v26, v26, v184
	v_mul_f32_e32 v27, v27, v184
	v_mul_f32_e32 v28, v28, v184
	v_mul_f32_e32 v29, v29, v184
	v_add_f32_e32 v174, 1.0, v174
	v_add_f32_e32 v175, 1.0, v175
	v_add_f32_e32 v176, 1.0, v176
	v_add_f32_e32 v177, 1.0, v177
	v_rcp_f32_e32 v174, v174
	v_rcp_f32_e32 v175, v175
	v_rcp_f32_e32 v176, v176
	v_rcp_f32_e32 v177, v177
	v_mul_f32_e32 v30, v30, v174
	v_mul_f32_e32 v31, v31, v175
	v_mul_f32_e32 v32, v32, v176
	v_mul_f32_e32 v33, v33, v177
	v_mul_f32_e32 v26, v26, v30
	v_mul_f32_e32 v27, v27, v31
	v_mul_f32_e32 v28, v28, v32
	v_mul_f32_e32 v29, v29, v33
	v_cvt_pk_bf16_f32 v26, v26, v27
	v_cvt_pk_bf16_f32 v27, v28, v29
	global_store_dwordx2 v186, v[26:27], s[14:15] offset:128
	s_add_u32 s14, s14, 0x16800
	s_addc_u32 s15, s15, 0
	v_mul_f32_e32 v10, v10, v185
	v_mul_f32_e32 v11, v11, v185
	v_mul_f32_e32 v12, v12, v185
	v_mul_f32_e32 v13, v13, v185
	v_mul_f32_e32 v174, 0xbfb8aa3b, v10
	v_mul_f32_e32 v175, 0xbfb8aa3b, v11
	v_mul_f32_e32 v176, 0xbfb8aa3b, v12
	v_mul_f32_e32 v177, 0xbfb8aa3b, v13
	v_exp_f32_e32 v174, v174
	v_exp_f32_e32 v175, v175
	v_exp_f32_e32 v176, v176
	v_exp_f32_e32 v177, v177
	v_mul_f32_e32 v2, v2, v185
	v_mul_f32_e32 v3, v3, v185
	v_mul_f32_e32 v4, v4, v185
	v_mul_f32_e32 v5, v5, v185
	v_add_f32_e32 v174, 1.0, v174
	v_add_f32_e32 v175, 1.0, v175
	v_add_f32_e32 v176, 1.0, v176
	v_add_f32_e32 v177, 1.0, v177
	v_rcp_f32_e32 v174, v174
	v_rcp_f32_e32 v175, v175
	v_rcp_f32_e32 v176, v176
	v_rcp_f32_e32 v177, v177
	v_mul_f32_e32 v10, v10, v174
	v_mul_f32_e32 v11, v11, v175
	v_mul_f32_e32 v12, v12, v176
	v_mul_f32_e32 v13, v13, v177
	v_mul_f32_e32 v2, v2, v10
	v_mul_f32_e32 v3, v3, v11
	v_mul_f32_e32 v4, v4, v12
	v_mul_f32_e32 v5, v5, v13
	v_cvt_pk_bf16_f32 v2, v2, v3
	v_cvt_pk_bf16_f32 v3, v4, v5
	global_store_dwordx2 v186, v[2:3], s[14:15]
	v_mul_f32_e32 v14, v14, v185
	v_mul_f32_e32 v15, v15, v185
	v_mul_f32_e32 v16, v16, v185
	v_mul_f32_e32 v17, v17, v185
	v_mul_f32_e32 v174, 0xbfb8aa3b, v14
	v_mul_f32_e32 v175, 0xbfb8aa3b, v15
	v_mul_f32_e32 v176, 0xbfb8aa3b, v16
	v_mul_f32_e32 v177, 0xbfb8aa3b, v17
	v_exp_f32_e32 v174, v174
	v_exp_f32_e32 v175, v175
	v_exp_f32_e32 v176, v176
	v_exp_f32_e32 v177, v177
	v_mul_f32_e32 v6, v6, v185
	v_mul_f32_e32 v7, v7, v185
	v_mul_f32_e32 v8, v8, v185
	v_mul_f32_e32 v9, v9, v185
	v_add_f32_e32 v174, 1.0, v174
	v_add_f32_e32 v175, 1.0, v175
	v_add_f32_e32 v176, 1.0, v176
	v_add_f32_e32 v177, 1.0, v177
	v_rcp_f32_e32 v174, v174
	v_rcp_f32_e32 v175, v175
	v_rcp_f32_e32 v176, v176
	v_rcp_f32_e32 v177, v177
	v_mul_f32_e32 v14, v14, v174
	v_mul_f32_e32 v15, v15, v175
	v_mul_f32_e32 v16, v16, v176
	v_mul_f32_e32 v17, v17, v177
	v_mul_f32_e32 v6, v6, v14
	v_mul_f32_e32 v7, v7, v15
	v_mul_f32_e32 v8, v8, v16
	v_mul_f32_e32 v9, v9, v17
	v_cvt_pk_bf16_f32 v6, v6, v7
	v_cvt_pk_bf16_f32 v7, v8, v9
	global_store_dwordx2 v186, v[6:7], s[14:15] offset:128
	s_and_b64 vcc, exec, s[12:13]
	s_cbranch_vccnz .Lup1_rr_skip
	v_cmp_gt_i32_e32 vcc, s34, v170
	s_and_saveexec_b64 s[18:19], vcc
	s_cbranch_execz .Lup1_rr_done
	s_lshl_b32 s15, s37, 10
	s_xor_b32 s15, s15, 0x400
	s_addk_i32 s15, 0x100
	v_lshl_add_u32 v130, v170, 2, s15
	v_add_u32_e32 v130, 0x20000, v130
	s_waitcnt vmcnt(22)
	v_mov_b32_e32 v132, v189
	v_mov_b32_e32 v133, v190
	v_mov_b32_e32 v189, v191
	v_mov_b32_e32 v190, v193
	v_mov_b32_e32 v191, v194
	v_mov_b32_e32 v193, v195
	v_pk_add_f32 v[132:133], v[132:133], v[188:189]
	v_pk_add_f32 v[188:189], v[190:191], v[192:193]
	v_pk_add_f32 v[132:133], v[132:133], v[132:133] op_sel:[0,1] op_sel_hi:[1,0]
	v_pk_add_f32 v[188:189], v[188:189], v[188:189] op_sel:[0,1] op_sel_hi:[1,0]
	v_add_f32_e32 v194, v196, v197
	v_add_f32_e32 v196, v198, v199
	v_mov_b32_e32 v195, v202
	v_mov_b32_e32 v197, v203
	v_mov_b32_e32 v133, v200
	v_mov_b32_e32 v189, v201
	v_pk_add_f32 v[190:191], v[194:195], v[196:197]
	v_pk_add_f32 v[132:133], v[132:133], v[188:189]
	s_nop 0
	v_pk_add_f32 v[132:133], v[132:133], v[190:191]
	s_nop 0
	v_add_f32_e32 v132, v132, v133
	v_fmamk_f32 v132, v132, 0x3a800000, v134
	v_mul_f32_e32 v133, 0x4b800000, v132
	v_cmp_gt_f32_e32 vcc, s39, v132
	s_nop 1
	v_cndmask_b32_e32 v132, v132, v133, vcc
	v_rsq_f32_e32 v132, v132
	s_nop 0
	v_mul_f32_e32 v133, 0x45800000, v132
	v_cndmask_b32_e32 v132, v132, v133, vcc
	ds_write_b32 v130, v132

; #define GAS __attribute__((address_space(1)))
; #define WAIT_V(n) asm volatile("s_waitcnt vmcnt(" #n ")" ::: "memory")
; #define BAR __builtin_amdgcn_s_barrier()
; template <int K, int LD = K>
; __device__ __forceinline__ void gemm_main(const GAS bf16* A, const GAS bf16* Bt, int brow, int bcol, f32x4 (&acc)[2][2][4][2]) {
;     ...
;   const int wid = tid_ >> 6, lane = tid_ & 63, wr = wid >> 2, wc = wid & 3, fr = lane & 15, fq = lane >> 4;
; #pragma unroll
;   for (int a = 0; a < 2; ++a)
; #pragma unroll
;     for (int b = 0; b < 2; ++b)
; #pragma unroll
;       for (int m = 0; m < 4; ++m)
; #pragma unroll
;         for (int n = 0; n < 2; ++n) acc[a][b][m][n] = f32x4{0.f, 0.f, 0.f, 0.f};
;   bf16x8 At[4][2], B0[2][2], B1[2][2];
;   unsigned so0, so1;
;   { int r_, c_; stage_rc(tid_ * 16, r_, c_); so0 = (unsigned)(r_ * LD + c_) * 2u; stage_rc(tid_ * 16 + 8192, r_, c_); so1 = (unsigned)(r_ * LD + c_) * 2u; }
;   const GAS char* pA0 = (const GAS char*)A + (long)brow * LD * 2; const GAS char* pA1 = pA0 + (long)HALF * LD * 2;
;   const GAS char* pB0 = (const GAS char*)Bt + (long)bcol * LD * 2; const GAS char* pB1 = pB0 + (long)HALF * LD * 2;
;   asm volatile("" : "+s"(pA0), "+s"(pA1), "+s"(pB0), "+s"(pB1));
;   constexpr int nt = K / BK;
;   static_assert(K % 128 == 0 && K >= 256, "K");
;   if (wr == 1) BAR;
;   WAIT_V(0); BAR;
;   BAR;
.LBB0_883:
	s_or_b64 exec, exec, s[22:23]
	v_bfe_i32 v7, v135, 27, 1
	v_lshlrev_b32_e32 v5, 4, v135
	v_lshrrev_b32_e32 v7, 22, v7
	v_add_u32_e32 v7, v5, v7
	v_and_b32_e32 v7, 0xfffffc00, v7
	v_sub_u32_e32 v7, v5, v7
	v_lshrrev_b32_e32 v8, 4, v7
	v_bitop3_b32 v8, v8, v7, 32 bitop3:0x6c
	v_ashrrev_i32_e32 v7, 31, v7
	v_ashrrev_i32_e32 v6, 31, v135
	v_lshrrev_b32_e32 v7, 26, v7
	v_lshrrev_b32_e32 v6, 26, v6
	v_add_u32_e32 v7, v8, v7
	v_add_u32_e32 v6, v135, v6
	v_ashrrev_i32_e32 v7, 6, v7
	v_ashrrev_i32_e32 v6, 6, v6
	v_mul_i32_i24_e32 v10, 64, v7
	v_lshlrev_b32_e32 v9, 3, v6
	v_lshlrev_b32_e32 v6, 5, v6
	v_sub_u32_e32 v8, v8, v10
	v_and_b32_e32 v9, 0x1ffff0, v9
	v_and_b32_e32 v6, 32, v6
	v_ashrrev_i16_sdwa v8, v1, sext(v8) dst_sel:DWORD dst_unused:UNUSED_PAD src0_sel:DWORD src1_sel:BYTE_0
	v_add_u32_sdwa v6, v6, sext(v8) dst_sel:DWORD dst_unused:UNUSED_PAD src0_sel:DWORD src1_sel:WORD_0
	v_add_lshl_u32 v7, v7, v9, 11
	v_lshl_add_u32 v130, v6, 1, v7
	v_add_u32_e32 v6, 0x2000, v5
	v_ashrrev_i32_e32 v7, 31, v6
	v_lshrrev_b32_e32 v7, 22, v7
	v_add_u32_e32 v7, v6, v7
	v_ashrrev_i32_e32 v7, 10, v7
	v_mul_i32_i24_e32 v8, 0x400, v7
	v_sub_u32_e32 v6, v6, v8
	v_lshrrev_b32_e32 v8, 4, v6
	v_bitop3_b32 v6, v8, v6, 32 bitop3:0x6c
	v_ashrrev_i32_e32 v9, 31, v6
	v_lshrrev_b32_e32 v9, 26, v9
	v_add_u32_e32 v9, v6, v9
	v_lshrrev_b32_e32 v10, 6, v9
	v_and_b32_e32 v9, 0xc0, v9
	v_lshlrev_b32_e32 v8, 3, v7
	v_lshlrev_b32_e32 v7, 5, v7
	v_sub_u32_e32 v6, v6, v9
	v_and_b32_e32 v8, 0x1ffff0, v8
	v_and_b32_e32 v7, 32, v7
	v_ashrrev_i16_sdwa v6, v1, sext(v6) dst_sel:DWORD dst_unused:UNUSED_PAD src0_sel:DWORD src1_sel:BYTE_0
	v_add_u32_sdwa v6, v7, sext(v6) dst_sel:DWORD dst_unused:UNUSED_PAD src0_sel:DWORD src1_sel:WORD_0
	v_add_lshl_u32 v7, v10, v8, 11
	v_and_b32_e32 v3, 15, v135
	v_lshl_add_u32 v132, v6, 1, v7
	v_lshlrev_b32_e32 v6, 2, v135
	v_and_b32_e32 v4, 48, v135
	v_lshlrev_b32_e32 v3, 6, v3
	v_and_b32_e32 v6, 32, v6
	v_lshlrev_b32_e32 v11, 6, v135
	s_waitcnt vmcnt(22)
	v_bitop3_b32 v3, v3, v6, v4 bitop3:0x36
	v_lshlrev_b32_e32 v13, 13, v2
	v_and_or_b32 v2, v11, s38, v4
	v_add_u32_e32 v7, s29, v3
	v_add_u32_e32 v8, s30, v3
	v_add_u32_e32 v9, s31, v3
	v_add_u32_e32 v10, s33, v3
	v_and_b32_e32 v12, 0x3000, v11
	v_add_u32_e32 v3, 0x100, v3
	v_xad_u32 v4, v2, v6, s34
	v_or_b32_e32 v6, 0x800, v13
	v_or_b32_e32 v11, 0x1000, v13
	v_or_b32_e32 v14, 0x1800, v13
	v_mov_b32_e32 v2, 0
	v_add_u32_e32 v146, 0x100, v5
	v_add_u32_e32 v152, s29, v5
	v_add_u32_e32 v154, s30, v5
	v_add_u32_e32 v156, s31, v5
	v_add_u32_e32 v158, s33, v5
	v_mov_b32_e32 v133, v131
	s_mov_b32 s15, -2
	v_add_u32_e32 v145, v7, v12
	v_add_u32_e32 v139, v3, v13
	v_add_u32_e32 v138, v4, v6
	v_add_u32_e32 v137, v4, v11
	v_add_u32_e32 v136, v4, v14
	v_add_u32_e32 v144, 0xc000, v146
	v_add_u32_e32 v143, 0xe000, v146
	v_add_u32_e32 v142, v8, v12
	v_add_u32_e32 v147, 0x2000, v146
	v_add_u32_e32 v141, v9, v12
	v_add_u32_e32 v148, 0x4000, v146
	v_add_u32_e32 v149, 0x6000, v146
	v_add_u32_e32 v140, v10, v12
	v_add_u32_e32 v150, 0x8000, v146
	v_add_u32_e32 v151, 0xa000, v146
	v_add_u32_e32 v153, 0x2000, v152
	v_add_u32_e32 v155, 0x2000, v154
	v_add_u32_e32 v157, 0x2000, v156
	v_add_u32_e32 v159, 0x2000, v158
	v_mov_b32_e32 v3, v2
	v_mov_b32_e32 v4, v2
	v_mov_b32_e32 v5, v2
	v_mov_b32_e32 v6, v2
	v_mov_b32_e32 v7, v2
	v_mov_b32_e32 v8, v2
	v_mov_b32_e32 v9, v2
	v_mov_b32_e32 v10, v2
	v_mov_b32_e32 v11, v2
	v_mov_b32_e32 v12, v2
	v_mov_b32_e32 v13, v2
	v_mov_b32_e32 v14, v2
	v_mov_b32_e32 v15, v2
	v_mov_b32_e32 v16, v2
	v_mov_b32_e32 v17, v2
	v_mov_b32_e32 v18, v2
	v_mov_b32_e32 v19, v2
	v_mov_b32_e32 v20, v2
	v_mov_b32_e32 v21, v2
	v_mov_b32_e32 v22, v2
	v_mov_b32_e32 v23, v2
	v_mov_b32_e32 v24, v2
	v_mov_b32_e32 v25, v2
	v_mov_b32_e32 v26, v2
	v_mov_b32_e32 v27, v2
	v_mov_b32_e32 v28, v2
	v_mov_b32_e32 v29, v2
	v_mov_b32_e32 v30, v2
	v_mov_b32_e32 v31, v2
	v_mov_b32_e32 v32, v2
	v_mov_b32_e32 v33, v2
	v_mov_b32_e32 v34, v2
	v_mov_b32_e32 v35, v2
	v_mov_b32_e32 v36, v2
	v_mov_b32_e32 v37, v2
	v_mov_b32_e32 v38, v2
	v_mov_b32_e32 v39, v2
	v_mov_b32_e32 v40, v2
	v_mov_b32_e32 v41, v2
	v_mov_b32_e32 v42, v2
	v_mov_b32_e32 v43, v2
	v_mov_b32_e32 v44, v2
	v_mov_b32_e32 v45, v2
	v_mov_b32_e32 v46, v2
	v_mov_b32_e32 v47, v2
	v_mov_b32_e32 v48, v2
	v_mov_b32_e32 v49, v2
	v_mov_b32_e32 v50, v2
	v_mov_b32_e32 v51, v2
	v_mov_b32_e32 v52, v2
	v_mov_b32_e32 v53, v2
	v_mov_b32_e32 v54, v2
	v_mov_b32_e32 v55, v2
	v_mov_b32_e32 v56, v2
	v_mov_b32_e32 v57, v2
	v_mov_b32_e32 v58, v2
	v_mov_b32_e32 v59, v2
	v_mov_b32_e32 v60, v2
	v_mov_b32_e32 v61, v2
	v_mov_b32_e32 v62, v2
	v_mov_b32_e32 v63, v2
	v_mov_b32_e32 v64, v2
	v_mov_b32_e32 v65, v2
	v_mov_b32_e32 v66, v2
	v_mov_b32_e32 v67, v2
	v_mov_b32_e32 v68, v2
	v_mov_b32_e32 v69, v2
	v_mov_b32_e32 v70, v2
	v_mov_b32_e32 v71, v2
	v_mov_b32_e32 v72, v2
	v_mov_b32_e32 v73, v2
	v_mov_b32_e32 v74, v2
	v_mov_b32_e32 v75, v2
	v_mov_b32_e32 v76, v2
	v_mov_b32_e32 v77, v2
	v_mov_b32_e32 v78, v2
	v_mov_b32_e32 v79, v2
	v_mov_b32_e32 v80, v2
	v_mov_b32_e32 v81, v2
	v_mov_b32_e32 v82, v2
	v_mov_b32_e32 v83, v2
	v_mov_b32_e32 v84, v2
	v_mov_b32_e32 v85, v2
	v_mov_b32_e32 v86, v2
	v_mov_b32_e32 v87, v2
	v_mov_b32_e32 v88, v2
	v_mov_b32_e32 v89, v2
	v_mov_b32_e32 v90, v2
	v_mov_b32_e32 v91, v2
	v_mov_b32_e32 v92, v2
	v_mov_b32_e32 v93, v2
	v_mov_b32_e32 v94, v2
	v_mov_b32_e32 v95, v2
	v_mov_b32_e32 v96, v2
	v_mov_b32_e32 v97, v2
	v_mov_b32_e32 v98, v2
	v_mov_b32_e32 v99, v2
	v_mov_b32_e32 v100, v2
	v_mov_b32_e32 v101, v2
	v_mov_b32_e32 v102, v2
	v_mov_b32_e32 v103, v2
	v_mov_b32_e32 v104, v2
	v_mov_b32_e32 v105, v2
	v_mov_b32_e32 v106, v2
	v_mov_b32_e32 v107, v2
	v_mov_b32_e32 v108, v2
	v_mov_b32_e32 v109, v2
	v_mov_b32_e32 v110, v2
	v_mov_b32_e32 v111, v2
	v_mov_b32_e32 v112, v2
	v_mov_b32_e32 v113, v2
	v_mov_b32_e32 v114, v2
	v_mov_b32_e32 v115, v2
	v_mov_b32_e32 v116, v2
	v_mov_b32_e32 v117, v2
	v_mov_b32_e32 v118, v2
	v_mov_b32_e32 v119, v2
	v_mov_b32_e32 v120, v2
	v_mov_b32_e32 v121, v2
	v_mov_b32_e32 v122, v2
	v_mov_b32_e32 v123, v2
	v_mov_b32_e32 v124, v2
	v_mov_b32_e32 v125, v2
	v_mov_b32_e32 v126, v2
	v_mov_b32_e32 v127, v2
	v_mov_b32_e32 v128, v2
	v_mov_b32_e32 v129, v2
	s_barrier
	s_barrier

; #define GAS __attribute__((address_space(1)))
; __device__ __forceinline__ int otid() { int t = threadIdx.x; asm volatile("" : "+v"(t)); return t; }
; #define STAGE(P, GP, ktrel) do { const GAS char* _g = (GP) + (ktrel) * (BK * 2); \
;     __builtin_amdgcn_global_load_lds((const GAS unsigned*)(_g + so0), (unsigned*)((char*)(P) + tid_ * 16), 16, 0, 0); \
;     __builtin_amdgcn_global_load_lds((const GAS unsigned*)(_g + so1), (unsigned*)((char*)(P) + tid_ * 16 + 8192), 16, 0, 0); } while (0)
; template <int K, int LD = K>
; __device__ __forceinline__ void gemm_prefetch(const GAS bf16* A, const GAS bf16* Bt, int brow, int bcol) {
;   bf16* shm = (bf16*)smem_raw;
;   const int tid_ = otid();
;   unsigned so0, so1;
;   { int r_, c_; stage_rc(tid_ * 16, r_, c_); so0 = (unsigned)(r_ * LD + c_) * 2u; stage_rc(tid_ * 16 + 8192, r_, c_); so1 = (unsigned)(r_ * LD + c_) * 2u; }
;   const GAS char* pA0 = (const GAS char*)A + (long)brow * LD * 2; const GAS char* pA1 = pA0 + (long)HALF * LD * 2;
;   const GAS char* pB0 = (const GAS char*)Bt + (long)bcol * LD * 2; const GAS char* pB1 = pB0 + (long)HALF * LD * 2;
;   asm volatile("" : "+s"(pA0), "+s"(pA1), "+s"(pB0), "+s"(pB1));
;   STAGE(SB(0, 0), pB0, 0); STAGE(SA(0, 0), pA0, 0);
;   STAGE(SB(0, 1), pB1, 0); STAGE(SA(0, 1), pA1, 0);
;   STAGE(SB(1, 0), pB0, 1); STAGE(SA(1, 0), pA0, 1); STAGE(SB(1, 1), pB1, 1);
; }
; __device__ __forceinline__ void load_rr(const GAS float* ssq, int brow, int par) {
;   float* rr = (float*)(smem_raw + LDS_RR) + par * 256;
;   const int tx = otid();
;   if (tx < 256) {
;     const GAS f32x4* s = (const GAS f32x4*)(ssq + (size_t)(brow + tx) * 16);
;     f32x4 a = s[0], b = s[1], c = s[2], d = s[3];
;     float t = ((a.x + a.y) + (a.z + a.w)) + ((b.x + b.y) + (b.z + b.w)) + ((c.x + c.y) + (c.z + c.w)) + ((d.x + d.y) + (d.z + d.w));
;     rr[tx] = rsqrtf(t * (1.f / DM) + EPS);
;   }
.LBB0_887:
	s_or_b64 exec, exec, s[12:13]
	v_readfirstlane_b32 s12, v171
	s_add_i32 s3, s12, s3
	s_cmpk_gt_i32 s3, 0x57f
	s_cselect_b64 s[12:13], -1, 0
	s_and_b64 vcc, exec, s[12:13]
	s_mov_b32 s20, s41
	s_cbranch_vccnz .LBB0_880
	v_mov_b32_e32 v130, v170
	s_mul_hi_i32 s15, s3, 0x2e8ba2e9
	v_ashrrev_i32_e32 v132, 31, v130
	v_lshrrev_b32_e32 v132, 26, v132
	v_lshlrev_b32_e32 v135, 4, v130
	v_add_u32_e32 v132, v130, v132
	v_bfe_i32 v130, v130, 27, 1
	v_lshrrev_b32_e32 v130, 22, v130
	v_add_u32_e32 v130, v135, v130
	v_and_b32_e32 v130, 0xfffffc00, v130
	v_sub_u32_e32 v130, v135, v130
	v_lshrrev_b32_e32 v133, 4, v130
	v_bitop3_b32 v133, v133, v130, 32 bitop3:0x6c
	v_ashrrev_i32_e32 v130, 31, v130
	v_lshrrev_b32_e32 v130, 26, v130
	v_add_u32_e32 v130, v133, v130
	v_ashrrev_i32_e32 v130, 6, v130
	v_ashrrev_i32_e32 v132, 6, v132
	v_mul_i32_i24_e32 v137, 64, v130
	v_lshlrev_b32_e32 v136, 3, v132
	v_lshlrev_b32_e32 v132, 5, v132
	v_sub_u32_e32 v133, v133, v137
	s_lshr_b32 s16, s15, 31
	s_ashr_i32 s15, s15, 5
	v_and_b32_e32 v136, 0x1ffff0, v136
	v_and_b32_e32 v132, 32, v132
	v_ashrrev_i16_sdwa v133, v1, sext(v133) dst_sel:DWORD dst_unused:UNUSED_PAD src0_sel:DWORD src1_sel:BYTE_0
	s_add_i32 s15, s15, s16
	v_add_u32_sdwa v132, v132, sext(v133) dst_sel:DWORD dst_unused:UNUSED_PAD src0_sel:DWORD src1_sel:WORD_0
	v_add_lshl_u32 v130, v130, v136, 11
	s_mul_i32 s16, s15, 0xb0
	v_lshl_add_u32 v130, v132, 1, v130
	v_add_u32_e32 v132, 0x2000, v135
	s_sub_i32 s16, s3, s16
	v_ashrrev_i32_e32 v133, 31, v132
	s_lshl_b32 s15, s15, 3
	s_and_b32 s17, s16, 7
	v_lshrrev_b32_e32 v133, 22, v133
	s_or_b32 s28, s17, s15
	v_add_u32_e32 v133, v132, v133
	s_ashr_i32 s20, s16, 3
	s_lshl_b32 s16, s28, 8
	v_ashrrev_i32_e32 v133, 10, v133
	v_mul_i32_i24_e32 v136, 0x400, v133
	s_ashr_i32 s17, s16, 31
	s_lshl_b32 s18, s20, 8
	v_sub_u32_e32 v132, v132, v136
	s_lshl_b64 s[22:23], s[16:17], 11
	v_lshrrev_b32_e32 v136, 4, v132
	s_add_u32 s22, s26, s22
	v_bitop3_b32 v132, v136, v132, 32 bitop3:0x6c
	s_addc_u32 s23, s27, s23
	v_ashrrev_i32_e32 v137, 31, v132
	s_add_u32 s42, s22, 0x40000
	v_lshrrev_b32_e32 v137, 26, v137
	s_addc_u32 s43, s23, 0
	s_ashr_i32 s19, s18, 31
	v_add_u32_e32 v137, v132, v137
	s_lshl_b64 s[18:19], s[18:19], 11
	v_lshrrev_b32_e32 v138, 6, v137
	v_and_b32_e32 v137, 0xc0, v137
	s_add_u32 s18, s24, s18
	v_lshlrev_b32_e32 v136, 3, v133
	v_lshlrev_b32_e32 v133, 5, v133
	v_sub_u32_e32 v132, v132, v137
	s_addc_u32 s19, s25, s19
	v_add_u32_e32 v140, s29, v135
	v_and_b32_e32 v136, 0x1ffff0, v136
	v_and_b32_e32 v133, 32, v133
	v_ashrrev_i16_sdwa v132, v1, sext(v132) dst_sel:DWORD dst_unused:UNUSED_PAD src0_sel:DWORD src1_sel:BYTE_0
	s_add_u32 s44, s18, 0x40000
	v_readfirstlane_b32 s15, v140
	v_add_u32_e32 v140, 0x2000, v140
	v_add_u32_sdwa v132, v133, sext(v132) dst_sel:DWORD dst_unused:UNUSED_PAD src0_sel:DWORD src1_sel:WORD_0
	v_add_lshl_u32 v133, v138, v136, 11
	s_addc_u32 s45, s19, 0
	s_mov_b32 m0, s15
	v_readfirstlane_b32 s15, v140
	v_add_u32_e32 v148, 0x100, v135
	v_lshl_add_u32 v132, v132, 1, v133
	v_add_u32_e32 v144, 0x2000, v148
	s_mov_b32 m0, s15
	v_readfirstlane_b32 s15, v148
	v_mov_b32_e32 v133, v131
	s_mov_b32 m0, s15
	v_readfirstlane_b32 s15, v144
	v_add_u32_e32 v149, s30, v135
	v_lshl_add_u64 v[138:139], s[18:19], 0, v[132:133]
	v_lshl_add_u64 v[142:143], s[22:23], 0, v[132:133]
	s_mov_b32 m0, s15
	v_readfirstlane_b32 s15, v149
	v_lshl_add_u64 v[146:147], s[44:45], 0, v[132:133]
	v_add_u32_e32 v133, 0x2000, v149
	s_mov_b32 m0, s15
	v_readfirstlane_b32 s15, v133
	v_add_u32_e32 v133, 0x4000, v148
	s_mov_b32 m0, s15
	v_readfirstlane_b32 s15, v133
	s_mov_b32 m0, s15
	v_lshl_add_u64 v[136:137], s[18:19], 0, v[130:131]
	v_lshl_add_u64 v[140:141], s[22:23], 0, v[130:131]
	v_lshl_add_u64 v[144:145], s[44:45], 0, v[130:131]
	v_add_u32_e32 v130, 0x6000, v148
	s_nop 0
	v_readfirstlane_b32 s15, v130
	v_add_u32_e32 v130, s31, v135
	s_mov_b32 m0, s15
	v_readfirstlane_b32 s15, v130
	v_add_u32_e32 v130, 0x2000, v130
	v_cmp_gt_i32_e32 vcc, s34, v170
	s_and_saveexec_b64 s[98:99], vcc
	v_add_u32_e32 v204, s16, v170
	v_ashrrev_i32_e32 v205, 31, v204
	v_lshlrev_b64 v[204:205], 6, v[204:205]
	v_lshl_add_u64 v[204:205], s[4:5], 0, v[204:205]
	global_load_dwordx4 v[188:191], v[204:205], off
	global_load_dwordx4 v[192:195], v[204:205], off offset:16
	global_load_dwordx4 v[196:199], v[204:205], off offset:32
	global_load_dwordx4 v[200:203], v[204:205], off offset:48
	s_or_b64 exec, exec, s[98:99]
	v_lshl_add_u64 v[132:133], v[136:137], 0, s[6:7]
	s_mov_b32 m0, s15
	v_readfirstlane_b32 s15, v130
	v_add_u32_e32 v130, 0x8000, v148
	global_load_lds_dwordx4 v[132:133], off
	v_lshl_add_u64 v[132:133], v[138:139], 0, s[6:7]
	s_mov_b32 m0, s15
	v_readfirstlane_b32 s15, v130
	v_add_u32_e32 v130, 0xa000, v148
	global_load_lds_dwordx4 v[132:133], off
	v_lshl_add_u64 v[132:133], v[140:141], 0, s[6:7]
	s_mov_b32 m0, s15
	v_readfirstlane_b32 s15, v130
	v_add_u32_e32 v130, s33, v135
	global_load_lds_dwordx4 v[132:133], off
	v_lshl_add_u64 v[132:133], v[142:143], 0, s[6:7]
	s_mov_b32 m0, s15
	v_readfirstlane_b32 s15, v130
	v_add_u32_e32 v130, 0x2000, v130
	global_load_lds_dwordx4 v[132:133], off
	v_lshl_add_u64 v[132:133], v[144:145], 0, s[6:7]
	s_mov_b32 m0, s15
	v_readfirstlane_b32 s15, v130
	global_load_lds_dwordx4 v[132:133], off
	v_lshl_add_u64 v[132:133], v[146:147], 0, s[6:7]
	s_mov_b32 m0, s15
	v_mov_b32_e32 v130, v170
	global_load_lds_dwordx4 v[132:133], off
	s_nop 0
	v_cmp_gt_i32_e32 vcc, s34, v130
	s_and_saveexec_b64 s[18:19], vcc
	s_cbranch_execz .LBB0_879
	v_add_u32_e32 v132, s16, v130
	v_ashrrev_i32_e32 v133, 31, v132
	v_lshlrev_b64 v[132:133], 6, v[132:133]
	v_lshl_add_u64 v[132:133], s[4:5], 0, v[132:133]
	s_branch .LBB0_879
